# p f32->bf16 conversion moved to the workgroups idle at the end of the input projection; conv loop no longer streams p
# speedup vs baseline: 1.0020x; 1.0020x over previous
; __device__ __forceinline__ unsigned cvt_pk_bf16(float lo, float hi) { unsigned r; asm volatile("v_cvt_pk_bf16_f32 %0, %1, %2" : "=v"(r) : "v"(lo), "v"(hi)); return r; }
; __global__ void __launch_bounds__(512, 2) trunk_fwd(Args args) {
;     ...
;                     u32x2 pw; pw.x = cvt_pk_bf16(pv4[0], pv4[1]); pw.y = cvt_pk_bf16(pv4[2], pv4[3]);
;                     *(u32x2*)(PB + (size_t)r * PLE + lane * 4) = pw;
.LBB0_507:
	v_readlane_b32 s4, v254, 2
	s_nop 3
	v_mov_b32_e32 v0, s4
	ds_read_b32 v0, v0
	s_waitcnt lgkmcnt(0)
	v_readfirstlane_b32 s4, v0
	v_readfirstlane_b32 s5, v163
	s_nop 3
	s_cmp_lt_u32 s4, 0x80
	s_cbranch_scc1 .Lpc_skip
	s_load_dwordx2 s[6:7], s[94:95], 0x8
	s_load_dwordx2 s[18:19], s[94:95], 0xc0
	s_lshr_b32 s5, s5, 6
	s_and_b32 s40, s4, 7
	s_lshr_b32 s4, s4, 3
	s_sub_u32 s4, s4, 16
	s_lshl_b32 s4, s4, 3
	s_add_u32 s4, s4, s5
	s_lshl_b32 s4, s4, 5
	s_lshl_b32 s40, s40, 12
	s_add_u32 s40, s40, s4
	s_mov_b32 s41, 0
	v_readlane_b32 s38, v254, 63
	s_mov_b32 s39, 0
	v_and_b32_e32 v2, 63, v163
	v_lshlrev_b32_e32 v3, 3, v2
	v_lshlrev_b32_e32 v2, 4, v2
	s_lshl_b64 s[38:39], s[38:39], 25
	s_lshl_b64 s[4:5], s[40:41], 10
	s_lshl_b64 s[40:41], s[40:41], 9
	s_waitcnt lgkmcnt(0)
	s_add_u32 s6, s6, s38
	s_addc_u32 s7, s7, s39
	s_add_u32 s6, s6, s4
	s_addc_u32 s7, s7, s5
	s_add_u32 s18, s18, 0x1d500000
	s_addc_u32 s19, s19, 0
	s_add_u32 s18, s18, s40
	s_addc_u32 s19, s19, s41
	global_load_dwordx4 v[4:7], v2, s[6:7]
	global_load_dwordx4 v[8:11], v2, s[6:7] offset:1024
	global_load_dwordx4 v[12:15], v2, s[6:7] offset:2048
	global_load_dwordx4 v[16:19], v2, s[6:7] offset:3072
	s_add_u32 s6, s6, 0x1000
	s_addc_u32 s7, s7, 0
	global_load_dwordx4 v[20:23], v2, s[6:7]
	global_load_dwordx4 v[24:27], v2, s[6:7] offset:1024
	global_load_dwordx4 v[28:31], v2, s[6:7] offset:2048
	global_load_dwordx4 v[32:35], v2, s[6:7] offset:3072
	s_add_u32 s6, s6, 0x1000
	s_addc_u32 s7, s7, 0
	s_waitcnt vmcnt(7)
	v_cvt_pk_bf16_f32 v4, v4, v5
	v_cvt_pk_bf16_f32 v5, v6, v7
	s_waitcnt vmcnt(6)
	v_cvt_pk_bf16_f32 v8, v8, v9
	v_cvt_pk_bf16_f32 v9, v10, v11
	s_waitcnt vmcnt(5)
	v_cvt_pk_bf16_f32 v12, v12, v13
	v_cvt_pk_bf16_f32 v13, v14, v15
	s_waitcnt vmcnt(4)
	v_cvt_pk_bf16_f32 v16, v16, v17
	v_cvt_pk_bf16_f32 v17, v18, v19
	s_waitcnt vmcnt(3)
	v_cvt_pk_bf16_f32 v20, v20, v21
	v_cvt_pk_bf16_f32 v21, v22, v23
	s_waitcnt vmcnt(2)
	v_cvt_pk_bf16_f32 v24, v24, v25
	v_cvt_pk_bf16_f32 v25, v26, v27
	s_waitcnt vmcnt(1)
	v_cvt_pk_bf16_f32 v28, v28, v29
	v_cvt_pk_bf16_f32 v29, v30, v31
	s_waitcnt vmcnt(0)
	v_cvt_pk_bf16_f32 v32, v32, v33
	v_cvt_pk_bf16_f32 v33, v34, v35
	global_store_dwordx2 v3, v[4:5], s[18:19]
	global_store_dwordx2 v3, v[8:9], s[18:19] offset:512
	global_store_dwordx2 v3, v[12:13], s[18:19] offset:1024
	global_store_dwordx2 v3, v[16:17], s[18:19] offset:1536
	global_store_dwordx2 v3, v[20:21], s[18:19] offset:2048
	global_store_dwordx2 v3, v[24:25], s[18:19] offset:2560
	global_store_dwordx2 v3, v[28:29], s[18:19] offset:3072
	global_store_dwordx2 v3, v[32:33], s[18:19] offset:3584
	s_add_u32 s18, s18, 0x1000
	s_addc_u32 s19, s19, 0
	global_load_dwordx4 v[4:7], v2, s[6:7]
	global_load_dwordx4 v[8:11], v2, s[6:7] offset:1024
	global_load_dwordx4 v[12:15], v2, s[6:7] offset:2048
	global_load_dwordx4 v[16:19], v2, s[6:7] offset:3072
	s_add_u32 s6, s6, 0x1000
	s_addc_u32 s7, s7, 0
	global_load_dwordx4 v[20:23], v2, s[6:7]
	global_load_dwordx4 v[24:27], v2, s[6:7] offset:1024
	global_load_dwordx4 v[28:31], v2, s[6:7] offset:2048
	global_load_dwordx4 v[32:35], v2, s[6:7] offset:3072
	s_add_u32 s6, s6, 0x1000
	s_addc_u32 s7, s7, 0
	s_waitcnt vmcnt(7)
	v_cvt_pk_bf16_f32 v4, v4, v5
	v_cvt_pk_bf16_f32 v5, v6, v7
	s_waitcnt vmcnt(6)
	v_cvt_pk_bf16_f32 v8, v8, v9
	v_cvt_pk_bf16_f32 v9, v10, v11
	s_waitcnt vmcnt(5)
	v_cvt_pk_bf16_f32 v12, v12, v13
	v_cvt_pk_bf16_f32 v13, v14, v15
	s_waitcnt vmcnt(4)
	v_cvt_pk_bf16_f32 v16, v16, v17
	v_cvt_pk_bf16_f32 v17, v18, v19
	s_waitcnt vmcnt(3)
	v_cvt_pk_bf16_f32 v20, v20, v21
	v_cvt_pk_bf16_f32 v21, v22, v23
	s_waitcnt vmcnt(2)
	v_cvt_pk_bf16_f32 v24, v24, v25
	v_cvt_pk_bf16_f32 v25, v26, v27
	s_waitcnt vmcnt(1)
	v_cvt_pk_bf16_f32 v28, v28, v29
	v_cvt_pk_bf16_f32 v29, v30, v31
	s_waitcnt vmcnt(0)
; __device__ __forceinline__ unsigned cvt_pk_bf16(float lo, float hi) { unsigned r; asm volatile("v_cvt_pk_bf16_f32 %0, %1, %2" : "=v"(r) : "v"(lo), "v"(hi)); return r; }
; __global__ void __launch_bounds__(512, 2) trunk_fwd(Args args) {
;     ...
;                     u32x2 pw; pw.x = cvt_pk_bf16(pv4[0], pv4[1]); pw.y = cvt_pk_bf16(pv4[2], pv4[3]);
;                     *(u32x2*)(PB + (size_t)r * PLE + lane * 4) = pw;
	v_cvt_pk_bf16_f32 v32, v32, v33
	v_cvt_pk_bf16_f32 v33, v34, v35
	global_store_dwordx2 v3, v[4:5], s[18:19]
	global_store_dwordx2 v3, v[8:9], s[18:19] offset:512
	global_store_dwordx2 v3, v[12:13], s[18:19] offset:1024
	global_store_dwordx2 v3, v[16:17], s[18:19] offset:1536
	global_store_dwordx2 v3, v[20:21], s[18:19] offset:2048
	global_store_dwordx2 v3, v[24:25], s[18:19] offset:2560
	global_store_dwordx2 v3, v[28:29], s[18:19] offset:3072
	global_store_dwordx2 v3, v[32:33], s[18:19] offset:3584
	s_add_u32 s18, s18, 0x1000
	s_addc_u32 s19, s19, 0
	global_load_dwordx4 v[4:7], v2, s[6:7]
	global_load_dwordx4 v[8:11], v2, s[6:7] offset:1024
	global_load_dwordx4 v[12:15], v2, s[6:7] offset:2048
	global_load_dwordx4 v[16:19], v2, s[6:7] offset:3072
	s_add_u32 s6, s6, 0x1000
	s_addc_u32 s7, s7, 0
	global_load_dwordx4 v[20:23], v2, s[6:7]
	global_load_dwordx4 v[24:27], v2, s[6:7] offset:1024
	global_load_dwordx4 v[28:31], v2, s[6:7] offset:2048
	global_load_dwordx4 v[32:35], v2, s[6:7] offset:3072
	s_add_u32 s6, s6, 0x1000
	s_addc_u32 s7, s7, 0
	s_waitcnt vmcnt(7)
	v_cvt_pk_bf16_f32 v4, v4, v5
	v_cvt_pk_bf16_f32 v5, v6, v7
	s_waitcnt vmcnt(6)
	v_cvt_pk_bf16_f32 v8, v8, v9
	v_cvt_pk_bf16_f32 v9, v10, v11
	s_waitcnt vmcnt(5)
	v_cvt_pk_bf16_f32 v12, v12, v13
	v_cvt_pk_bf16_f32 v13, v14, v15
	s_waitcnt vmcnt(4)
	v_cvt_pk_bf16_f32 v16, v16, v17
	v_cvt_pk_bf16_f32 v17, v18, v19
	s_waitcnt vmcnt(3)
	v_cvt_pk_bf16_f32 v20, v20, v21
	v_cvt_pk_bf16_f32 v21, v22, v23
	s_waitcnt vmcnt(2)
	v_cvt_pk_bf16_f32 v24, v24, v25
	v_cvt_pk_bf16_f32 v25, v26, v27
	s_waitcnt vmcnt(1)
	v_cvt_pk_bf16_f32 v28, v28, v29
	v_cvt_pk_bf16_f32 v29, v30, v31
	s_waitcnt vmcnt(0)
	v_cvt_pk_bf16_f32 v32, v32, v33
	v_cvt_pk_bf16_f32 v33, v34, v35
	global_store_dwordx2 v3, v[4:5], s[18:19]
	global_store_dwordx2 v3, v[8:9], s[18:19] offset:512
	global_store_dwordx2 v3, v[12:13], s[18:19] offset:1024
	global_store_dwordx2 v3, v[16:17], s[18:19] offset:1536
	global_store_dwordx2 v3, v[20:21], s[18:19] offset:2048
	global_store_dwordx2 v3, v[24:25], s[18:19] offset:2560
	global_store_dwordx2 v3, v[28:29], s[18:19] offset:3072
	global_store_dwordx2 v3, v[32:33], s[18:19] offset:3584
	s_add_u32 s18, s18, 0x1000
	s_addc_u32 s19, s19, 0
	global_load_dwordx4 v[4:7], v2, s[6:7]
	global_load_dwordx4 v[8:11], v2, s[6:7] offset:1024
	global_load_dwordx4 v[12:15], v2, s[6:7] offset:2048
	global_load_dwordx4 v[16:19], v2, s[6:7] offset:3072
	s_add_u32 s6, s6, 0x1000
	s_addc_u32 s7, s7, 0
	global_load_dwordx4 v[20:23], v2, s[6:7]
	global_load_dwordx4 v[24:27], v2, s[6:7] offset:1024
	global_load_dwordx4 v[28:31], v2, s[6:7] offset:2048
	global_load_dwordx4 v[32:35], v2, s[6:7] offset:3072
	s_add_u32 s6, s6, 0x1000
	s_addc_u32 s7, s7, 0
	s_waitcnt vmcnt(7)
	v_cvt_pk_bf16_f32 v4, v4, v5
	v_cvt_pk_bf16_f32 v5, v6, v7
	s_waitcnt vmcnt(6)
	v_cvt_pk_bf16_f32 v8, v8, v9
	v_cvt_pk_bf16_f32 v9, v10, v11
	s_waitcnt vmcnt(5)
	v_cvt_pk_bf16_f32 v12, v12, v13
	v_cvt_pk_bf16_f32 v13, v14, v15
	s_waitcnt vmcnt(4)
	v_cvt_pk_bf16_f32 v16, v16, v17
	v_cvt_pk_bf16_f32 v17, v18, v19
	s_waitcnt vmcnt(3)
	v_cvt_pk_bf16_f32 v20, v20, v21
	v_cvt_pk_bf16_f32 v21, v22, v23
	s_waitcnt vmcnt(2)
	v_cvt_pk_bf16_f32 v24, v24, v25
	v_cvt_pk_bf16_f32 v25, v26, v27
	s_waitcnt vmcnt(1)
	v_cvt_pk_bf16_f32 v28, v28, v29
	v_cvt_pk_bf16_f32 v29, v30, v31
	s_waitcnt vmcnt(0)
	v_cvt_pk_bf16_f32 v32, v32, v33
	v_cvt_pk_bf16_f32 v33, v34, v35
	global_store_dwordx2 v3, v[4:5], s[18:19]
	global_store_dwordx2 v3, v[8:9], s[18:19] offset:512
	global_store_dwordx2 v3, v[12:13], s[18:19] offset:1024
	global_store_dwordx2 v3, v[16:17], s[18:19] offset:1536
	global_store_dwordx2 v3, v[20:21], s[18:19] offset:2048
	global_store_dwordx2 v3, v[24:25], s[18:19] offset:2560
	global_store_dwordx2 v3, v[28:29], s[18:19] offset:3072
	global_store_dwordx2 v3, v[32:33], s[18:19] offset:3584
	s_add_u32 s18, s18, 0x1000
	s_addc_u32 s19, s19, 0

; __device__ __forceinline__ unsigned cvt_pk_bf16(float lo, float hi) { unsigned r; asm volatile("v_cvt_pk_bf16_f32 %0, %1, %2" : "=v"(r) : "v"(lo), "v"(hi)); return r; }
; __device__ __forceinline__ float bf_lo(unsigned w) { return __uint_as_float(w << 16); }
; __device__ __forceinline__ float bf_hi(unsigned w) { return __uint_as_float(w & 0xffff0000u); }
; __global__ void __launch_bounds__(512, 2) trunk_fwd(Args args) {
;     ...
;                 for (int rr = 0; rr < 16; ++rr) {
;                     const int r = r0 + rr;
;                     const u32x4 gb = gb_n, gu = gu_n; const f32x4 pv4 = pv_n;
;                     if (rr < 15) { gb_n = *(const u32x4*)(Z + (size_t)(r + 1) * INP + 768 + c0); gu_n = *(const u32x4*)(Z + (size_t)(r + 1) * INP + 1280 + c0);
;                                    pv_n = *(const f32x4*)(pl + (size_t)(r + 1) * PLE + lane * 4); }
;                     float cv[8], uu[8]; float ss = 0.f;
; #pragma unroll
;                     for (int i = 0; i < 4; ++i) {
;                         uu[2 * i] = bf_lo(gu[i]); uu[2 * i + 1] = bf_hi(gu[i]);
;                         cv[2 * i] = bf_lo(gb[i]) * (w0[2 * i] * uu[2 * i] + w1[2 * i] * u1[2 * i] + w2[2 * i] * u2[2 * i]);
;                         cv[2 * i + 1] = bf_hi(gb[i]) * (w0[2 * i + 1] * uu[2 * i + 1] + w1[2 * i + 1] * u1[2 * i + 1] + w2[2 * i + 1] * u2[2 * i + 1]);
;                     }
; #pragma unroll
;                     for (int i = 0; i < 8; ++i) { ss += cv[i] * cv[i]; u2[i] = u1[i]; u1[i] = uu[i]; }
;                     ss = wave_sum(ss);
;                     const float rc = rsqrtf(ss * (1.0f / 512.0f) + EPS);
;                     u32x4 oc;
; #pragma unroll
;                     for (int i = 0; i < 4; ++i) oc[i] = cvt_pk_bf16(cv[2 * i] * rc, cv[2 * i + 1] * rc);
;                     *(u32x4*)(MIX + (size_t)r * 1024 + 512 + c0) = oc;
;                     u32x2 pw; pw.x = cvt_pk_bf16(pv4[0], pv4[1]); pw.y = cvt_pk_bf16(pv4[2], pv4[3]);
;                     *(u32x2*)(PB + (size_t)r * PLE + lane * 4) = pw;
;                 }
.Lcv_taps_ok:
	v_mad_i64_i32 v[152:153], vcc, s41, v221, v[58:59]
	s_add_u32 s41, s41, 1
	global_load_dwordx4 v[2:5], v[152:153], off offset:1536
	global_load_dwordx4 v[18:21], v[152:153], off offset:2560
	v_mad_i64_i32 v[152:153], vcc, s41, v221, v[58:59]
	s_add_u32 s41, s41, 1
	global_load_dwordx4 v[6:9], v[152:153], off offset:1536
	global_load_dwordx4 v[22:25], v[152:153], off offset:2560
	v_mad_i64_i32 v[152:153], vcc, s41, v221, v[58:59]
	s_add_u32 s41, s41, 1
	global_load_dwordx4 v[10:13], v[152:153], off offset:1536
	global_load_dwordx4 v[26:29], v[152:153], off offset:2560
	v_mad_i64_i32 v[152:153], vcc, s41, v221, v[58:59]
	s_add_u32 s41, s41, 1
	global_load_dwordx4 v[14:17], v[152:153], off offset:1536
	global_load_dwordx4 v[30:33], v[152:153], off offset:2560
	s_waitcnt vmcnt(6)
	v_lshlrev_b32_e32 v188, 16, v18
	v_and_b32_e32 v189, 0xffff0000, v18
	v_lshlrev_b32_e32 v190, 16, v19
	v_and_b32_e32 v191, 0xffff0000, v19
	v_lshlrev_b32_e32 v192, 16, v20
	v_and_b32_e32 v193, 0xffff0000, v20
	v_lshlrev_b32_e32 v194, 16, v21
	v_and_b32_e32 v195, 0xffff0000, v21
	v_mul_f32_e32 v140, v164, v188
	v_mul_f32_e32 v141, v165, v189
	v_mul_f32_e32 v142, v166, v190
	v_mul_f32_e32 v143, v167, v191
	v_mul_f32_e32 v144, v168, v192
	v_mul_f32_e32 v145, v169, v193
	v_mul_f32_e32 v146, v170, v194
	v_mul_f32_e32 v147, v171, v195
	v_fmac_f32_e32 v140, v172, v204
	v_fmac_f32_e32 v141, v173, v205
	v_fmac_f32_e32 v142, v174, v206
	v_fmac_f32_e32 v143, v175, v207
	v_fmac_f32_e32 v144, v176, v208
	v_fmac_f32_e32 v145, v177, v209
	v_fmac_f32_e32 v146, v178, v210
	v_fmac_f32_e32 v147, v179, v211
	v_fmac_f32_e32 v140, v180, v196
	v_fmac_f32_e32 v141, v181, v197
	v_fmac_f32_e32 v142, v182, v198
	v_fmac_f32_e32 v143, v183, v199
	v_fmac_f32_e32 v144, v184, v200
	v_fmac_f32_e32 v145, v185, v201
	v_fmac_f32_e32 v146, v186, v202
	v_fmac_f32_e32 v147, v187, v203
	v_lshlrev_b32_e32 v150, 16, v2
	v_and_b32_e32 v151, 0xffff0000, v2
	v_mul_f32_e32 v140, v150, v140
	v_mul_f32_e32 v141, v151, v141
	v_lshlrev_b32_e32 v150, 16, v3
	v_and_b32_e32 v151, 0xffff0000, v3
	v_mul_f32_e32 v142, v150, v142
	v_mul_f32_e32 v143, v151, v143
	v_lshlrev_b32_e32 v150, 16, v4
	v_and_b32_e32 v151, 0xffff0000, v4
	v_mul_f32_e32 v144, v150, v144
	v_mul_f32_e32 v145, v151, v145
	v_lshlrev_b32_e32 v150, 16, v5
	v_and_b32_e32 v151, 0xffff0000, v5
	v_mul_f32_e32 v146, v150, v146
	v_mul_f32_e32 v147, v151, v147
	v_mul_f32_e32 v148, v140, v140
	v_fmac_f32_e32 v148, v141, v141
	v_fmac_f32_e32 v148, v142, v142
	v_fmac_f32_e32 v148, v143, v143
	v_fmac_f32_e32 v148, v144, v144
	v_fmac_f32_e32 v148, v145, v145
	v_fmac_f32_e32 v148, v146, v146
	v_fmac_f32_e32 v148, v147, v147
	v_mad_i64_i32 v[152:153], vcc, s41, v221, v[58:59]
	s_add_u32 s41, s41, 1
	global_load_dwordx4 v[2:5], v[152:153], off offset:1536
	global_load_dwordx4 v[18:21], v[152:153], off offset:2560
	ds_bpermute_b32 v150, v80, v148
	s_waitcnt lgkmcnt(0)
	v_add_f32_e32 v148, v148, v150
	ds_bpermute_b32 v150, v81, v148
	s_waitcnt lgkmcnt(0)
	v_add_f32_e32 v148, v148, v150
	ds_bpermute_b32 v150, v82, v148
	s_waitcnt lgkmcnt(0)
	v_add_f32_e32 v148, v148, v150
	ds_bpermute_b32 v150, v83, v148
	s_waitcnt lgkmcnt(0)
	v_add_f32_e32 v148, v148, v150
	ds_bpermute_b32 v150, v84, v148
	s_waitcnt lgkmcnt(0)
	v_add_f32_e32 v148, v148, v150
	ds_bpermute_b32 v150, v85, v148
	s_waitcnt lgkmcnt(0)
	v_add_f32_e32 v148, v148, v150
	v_fmamk_f32 v148, v148, 0x3b000000, v162
	v_mul_f32_e32 v150, 0x4b800000, v148
	v_cmp_gt_f32_e32 vcc, s31, v148
	s_nop 1
	v_cndmask_b32_e32 v148, v148, v150, vcc
	v_rsq_f32_e32 v148, v148
	s_nop 0
	v_mul_f32_e32 v150, 0x45800000, v148
	v_cndmask_b32_e32 v149, v148, v150, vcc
	v_mul_f32_e32 v140, v149, v140
	v_mul_f32_e32 v141, v149, v141
	v_mul_f32_e32 v142, v149, v142
	v_mul_f32_e32 v143, v149, v143
	v_mul_f32_e32 v144, v149, v144
	v_mul_f32_e32 v145, v149, v145
	v_mul_f32_e32 v146, v149, v146
	v_mul_f32_e32 v147, v149, v147
	v_cvt_pk_bf16_f32 v140, v140, v141
	v_cvt_pk_bf16_f32 v141, v142, v143
	v_cvt_pk_bf16_f32 v142, v144, v145
	v_cvt_pk_bf16_f32 v143, v146, v147
	global_store_dwordx4 v[156:157], v[140:143], off
	s_waitcnt vmcnt(7)
	v_lshlrev_b32_e32 v196, 16, v22
	v_and_b32_e32 v197, 0xffff0000, v22
	v_lshlrev_b32_e32 v198, 16, v23
	v_and_b32_e32 v199, 0xffff0000, v23
	v_lshlrev_b32_e32 v200, 16, v24
	v_and_b32_e32 v201, 0xffff0000, v24
	v_lshlrev_b32_e32 v202, 16, v25
	v_and_b32_e32 v203, 0xffff0000, v25
	v_mul_f32_e32 v140, v164, v196
	v_mul_f32_e32 v141, v165, v197
	v_mul_f32_e32 v142, v166, v198
	v_mul_f32_e32 v143, v167, v199
	v_mul_f32_e32 v144, v168, v200
	v_mul_f32_e32 v145, v169, v201
	v_mul_f32_e32 v146, v170, v202
	v_mul_f32_e32 v147, v171, v203
	v_fmac_f32_e32 v140, v172, v188
	v_fmac_f32_e32 v141, v173, v189
	v_fmac_f32_e32 v142, v174, v190
	v_fmac_f32_e32 v143, v175, v191
	v_fmac_f32_e32 v144, v176, v192
	v_fmac_f32_e32 v145, v177, v193
	v_fmac_f32_e32 v146, v178, v194
	v_fmac_f32_e32 v147, v179, v195
	v_fmac_f32_e32 v140, v180, v204
	v_fmac_f32_e32 v141, v181, v205
	v_fmac_f32_e32 v142, v182, v206
	v_fmac_f32_e32 v143, v183, v207
	v_fmac_f32_e32 v144, v184, v208
	v_fmac_f32_e32 v145, v185, v209
	v_fmac_f32_e32 v146, v186, v210
	v_fmac_f32_e32 v147, v187, v211
	v_lshlrev_b32_e32 v150, 16, v6
	v_and_b32_e32 v151, 0xffff0000, v6
	v_mul_f32_e32 v140, v150, v140
	v_mul_f32_e32 v141, v151, v141
	v_lshlrev_b32_e32 v150, 16, v7
	v_and_b32_e32 v151, 0xffff0000, v7
	v_mul_f32_e32 v142, v150, v142
	v_mul_f32_e32 v143, v151, v143
	v_lshlrev_b32_e32 v150, 16, v8
	v_and_b32_e32 v151, 0xffff0000, v8
	v_mul_f32_e32 v144, v150, v144
	v_mul_f32_e32 v145, v151, v145
	v_lshlrev_b32_e32 v150, 16, v9
	v_and_b32_e32 v151, 0xffff0000, v9
	v_mul_f32_e32 v146, v150, v146
	v_mul_f32_e32 v147, v151, v147
	v_mul_f32_e32 v148, v140, v140
	v_fmac_f32_e32 v148, v141, v141
	v_fmac_f32_e32 v148, v142, v142
	v_fmac_f32_e32 v148, v143, v143
	v_fmac_f32_e32 v148, v144, v144
	v_fmac_f32_e32 v148, v145, v145
	v_fmac_f32_e32 v148, v146, v146
	v_fmac_f32_e32 v148, v147, v147
	v_mad_i64_i32 v[152:153], vcc, s41, v221, v[58:59]
	s_add_u32 s41, s41, 1
	global_load_dwordx4 v[6:9], v[152:153], off offset:1536
	global_load_dwordx4 v[22:25], v[152:153], off offset:2560
	ds_bpermute_b32 v150, v80, v148
	s_waitcnt lgkmcnt(0)
; __device__ __forceinline__ unsigned cvt_pk_bf16(float lo, float hi) { unsigned r; asm volatile("v_cvt_pk_bf16_f32 %0, %1, %2" : "=v"(r) : "v"(lo), "v"(hi)); return r; }
; __device__ __forceinline__ float bf_lo(unsigned w) { return __uint_as_float(w << 16); }
; __device__ __forceinline__ float bf_hi(unsigned w) { return __uint_as_float(w & 0xffff0000u); }
; __global__ void __launch_bounds__(512, 2) trunk_fwd(Args args) {
;     ...
;                 for (int rr = 0; rr < 16; ++rr) {
;                     const int r = r0 + rr;
;                     const u32x4 gb = gb_n, gu = gu_n; const f32x4 pv4 = pv_n;
;                     if (rr < 15) { gb_n = *(const u32x4*)(Z + (size_t)(r + 1) * INP + 768 + c0); gu_n = *(const u32x4*)(Z + (size_t)(r + 1) * INP + 1280 + c0);
;                                    pv_n = *(const f32x4*)(pl + (size_t)(r + 1) * PLE + lane * 4); }
;                     float cv[8], uu[8]; float ss = 0.f;
; #pragma unroll
;                     for (int i = 0; i < 4; ++i) {
;                         uu[2 * i] = bf_lo(gu[i]); uu[2 * i + 1] = bf_hi(gu[i]);
;                         cv[2 * i] = bf_lo(gb[i]) * (w0[2 * i] * uu[2 * i] + w1[2 * i] * u1[2 * i] + w2[2 * i] * u2[2 * i]);
;                         cv[2 * i + 1] = bf_hi(gb[i]) * (w0[2 * i + 1] * uu[2 * i + 1] + w1[2 * i + 1] * u1[2 * i + 1] + w2[2 * i + 1] * u2[2 * i + 1]);
;                     }
; #pragma unroll
;                     for (int i = 0; i < 8; ++i) { ss += cv[i] * cv[i]; u2[i] = u1[i]; u1[i] = uu[i]; }
;                     ss = wave_sum(ss);
;                     const float rc = rsqrtf(ss * (1.0f / 512.0f) + EPS);
;                     u32x4 oc;
; #pragma unroll
;                     for (int i = 0; i < 4; ++i) oc[i] = cvt_pk_bf16(cv[2 * i] * rc, cv[2 * i + 1] * rc);
;                     *(u32x4*)(MIX + (size_t)r * 1024 + 512 + c0) = oc;
;                     u32x2 pw; pw.x = cvt_pk_bf16(pv4[0], pv4[1]); pw.y = cvt_pk_bf16(pv4[2], pv4[3]);
;                     *(u32x2*)(PB + (size_t)r * PLE + lane * 4) = pw;
;                 }
	v_add_f32_e32 v148, v148, v150
	ds_bpermute_b32 v150, v81, v148
	s_waitcnt lgkmcnt(0)
	v_add_f32_e32 v148, v148, v150
	ds_bpermute_b32 v150, v82, v148
	s_waitcnt lgkmcnt(0)
	v_add_f32_e32 v148, v148, v150
	ds_bpermute_b32 v150, v83, v148
	s_waitcnt lgkmcnt(0)
	v_add_f32_e32 v148, v148, v150
	ds_bpermute_b32 v150, v84, v148
	s_waitcnt lgkmcnt(0)
	v_add_f32_e32 v148, v148, v150
	ds_bpermute_b32 v150, v85, v148
	s_waitcnt lgkmcnt(0)
	v_add_f32_e32 v148, v148, v150
	v_fmamk_f32 v148, v148, 0x3b000000, v162
	v_mul_f32_e32 v150, 0x4b800000, v148
	v_cmp_gt_f32_e32 vcc, s31, v148
	s_nop 1
	v_cndmask_b32_e32 v148, v148, v150, vcc
	v_rsq_f32_e32 v148, v148
	s_nop 0
	v_mul_f32_e32 v150, 0x45800000, v148
	v_cndmask_b32_e32 v149, v148, v150, vcc
	v_mul_f32_e32 v140, v149, v140
	v_mul_f32_e32 v141, v149, v141
	v_mul_f32_e32 v142, v149, v142
	v_mul_f32_e32 v143, v149, v143
	v_mul_f32_e32 v144, v149, v144
	v_mul_f32_e32 v145, v149, v145
	v_mul_f32_e32 v146, v149, v146
	v_mul_f32_e32 v147, v149, v147
	v_cvt_pk_bf16_f32 v140, v140, v141
	v_cvt_pk_bf16_f32 v141, v142, v143
	v_cvt_pk_bf16_f32 v142, v144, v145
	v_cvt_pk_bf16_f32 v143, v146, v147
	global_store_dwordx4 v[156:157], v[140:143], off offset:2048
	v_lshl_add_u64 v[156:157], v[156:157], 0, s[20:21]
	s_waitcnt vmcnt(8)
	v_lshlrev_b32_e32 v204, 16, v26
	v_and_b32_e32 v205, 0xffff0000, v26
	v_lshlrev_b32_e32 v206, 16, v27
	v_and_b32_e32 v207, 0xffff0000, v27
	v_lshlrev_b32_e32 v208, 16, v28
	v_and_b32_e32 v209, 0xffff0000, v28
	v_lshlrev_b32_e32 v210, 16, v29
	v_and_b32_e32 v211, 0xffff0000, v29
	v_mul_f32_e32 v140, v164, v204
	v_mul_f32_e32 v141, v165, v205
	v_mul_f32_e32 v142, v166, v206
	v_mul_f32_e32 v143, v167, v207
	v_mul_f32_e32 v144, v168, v208
	v_mul_f32_e32 v145, v169, v209
	v_mul_f32_e32 v146, v170, v210
	v_mul_f32_e32 v147, v171, v211
	v_fmac_f32_e32 v140, v172, v196
	v_fmac_f32_e32 v141, v173, v197
	v_fmac_f32_e32 v142, v174, v198
	v_fmac_f32_e32 v143, v175, v199
	v_fmac_f32_e32 v144, v176, v200
	v_fmac_f32_e32 v145, v177, v201
	v_fmac_f32_e32 v146, v178, v202
	v_fmac_f32_e32 v147, v179, v203
	v_fmac_f32_e32 v140, v180, v188
	v_fmac_f32_e32 v141, v181, v189
	v_fmac_f32_e32 v142, v182, v190
	v_fmac_f32_e32 v143, v183, v191
	v_fmac_f32_e32 v144, v184, v192
	v_fmac_f32_e32 v145, v185, v193
	v_fmac_f32_e32 v146, v186, v194
	v_fmac_f32_e32 v147, v187, v195
	v_lshlrev_b32_e32 v150, 16, v10
	v_and_b32_e32 v151, 0xffff0000, v10
	v_mul_f32_e32 v140, v150, v140
	v_mul_f32_e32 v141, v151, v141
	v_lshlrev_b32_e32 v150, 16, v11
	v_and_b32_e32 v151, 0xffff0000, v11
	v_mul_f32_e32 v142, v150, v142
	v_mul_f32_e32 v143, v151, v143
	v_lshlrev_b32_e32 v150, 16, v12
	v_and_b32_e32 v151, 0xffff0000, v12
	v_mul_f32_e32 v144, v150, v144
	v_mul_f32_e32 v145, v151, v145
	v_lshlrev_b32_e32 v150, 16, v13
	v_and_b32_e32 v151, 0xffff0000, v13
	v_mul_f32_e32 v146, v150, v146
	v_mul_f32_e32 v147, v151, v147
	v_mul_f32_e32 v148, v140, v140
	v_fmac_f32_e32 v148, v141, v141
	v_fmac_f32_e32 v148, v142, v142
	v_fmac_f32_e32 v148, v143, v143
	v_fmac_f32_e32 v148, v144, v144
	v_fmac_f32_e32 v148, v145, v145
	v_fmac_f32_e32 v148, v146, v146
	v_fmac_f32_e32 v148, v147, v147
	v_mad_i64_i32 v[152:153], vcc, s41, v221, v[58:59]
	s_add_u32 s41, s41, 1
	global_load_dwordx4 v[10:13], v[152:153], off offset:1536
	global_load_dwordx4 v[26:29], v[152:153], off offset:2560
	ds_bpermute_b32 v150, v80, v148
	s_waitcnt lgkmcnt(0)
	v_add_f32_e32 v148, v148, v150
	ds_bpermute_b32 v150, v81, v148
	s_waitcnt lgkmcnt(0)
	v_add_f32_e32 v148, v148, v150
	ds_bpermute_b32 v150, v82, v148
	s_waitcnt lgkmcnt(0)
	v_add_f32_e32 v148, v148, v150
	ds_bpermute_b32 v150, v83, v148
	s_waitcnt lgkmcnt(0)
	v_add_f32_e32 v148, v148, v150
	ds_bpermute_b32 v150, v84, v148
	s_waitcnt lgkmcnt(0)
	v_add_f32_e32 v148, v148, v150
	ds_bpermute_b32 v150, v85, v148
	s_waitcnt lgkmcnt(0)
	v_add_f32_e32 v148, v148, v150
	v_fmamk_f32 v148, v148, 0x3b000000, v162
	v_mul_f32_e32 v150, 0x4b800000, v148
	v_cmp_gt_f32_e32 vcc, s31, v148
	s_nop 1
	v_cndmask_b32_e32 v148, v148, v150, vcc
	v_rsq_f32_e32 v148, v148
	s_nop 0
	v_mul_f32_e32 v150, 0x45800000, v148
	v_cndmask_b32_e32 v149, v148, v150, vcc
	v_mul_f32_e32 v140, v149, v140
	v_mul_f32_e32 v141, v149, v141
	v_mul_f32_e32 v142, v149, v142
	v_mul_f32_e32 v143, v149, v143
	v_mul_f32_e32 v144, v149, v144
	v_mul_f32_e32 v145, v149, v145
	v_mul_f32_e32 v146, v149, v146
	v_mul_f32_e32 v147, v149, v147
	v_cvt_pk_bf16_f32 v140, v140, v141
	v_cvt_pk_bf16_f32 v141, v142, v143
	v_cvt_pk_bf16_f32 v142, v144, v145
	v_cvt_pk_bf16_f32 v143, v146, v147
	global_store_dwordx4 v[156:157], v[140:143], off
	s_waitcnt vmcnt(9)
; __device__ __forceinline__ float bf_lo(unsigned w) { return __uint_as_float(w << 16); }
; __global__ void __launch_bounds__(512, 2) trunk_fwd(Args args) {
;     ...
;             for (int ch = gw; ch < M / 16; ch += NGW) {
;                 const int r0 = ch * 16, t0 = r0 & (SEQ - 1), c0 = lane * 8;
;                 float w0[8], w1[8], w2[8], u1[8], u2[8];
; #pragma unroll
;                 for (int i = 0; i < 8; ++i) { w0[i] = cw[c0 + i]; w1[i] = cw[512 + c0 + i]; w2[i] = cw[1024 + c0 + i]; u1[i] = 0.f; u2[i] = 0.f; }
;                 if (t0 != 0) {
;                     const u32x4 c1 = *(const u32x4*)(Z + (size_t)(r0 - 1) * INP + 1280 + c0), c2 = *(const u32x4*)(Z + (size_t)(r0 - 2) * INP + 1280 + c0);
; #pragma unroll
;                     for (int i = 0; i < 4; ++i) { u1[2 * i] = bf_lo(c1[i]); u1[2 * i + 1] = bf_hi(c1[i]); u2[2 * i] = bf_lo(c2[i]); u2[2 * i + 1] = bf_hi(c2[i]); }
;                 }
;                 u32x4 gb_n = *(const u32x4*)(Z + (size_t)r0 * INP + 768 + c0), gu_n = *(const u32x4*)(Z + (size_t)r0 * INP + 1280 + c0);
;                 f32x4 pv_n = *(const f32x4*)(pl + (size_t)r0 * PLE + lane * 4);
; #pragma nounroll
;                 for (int rr = 0; rr < 16; ++rr) {
;                     const int r = r0 + rr;
;                     const u32x4 gb = gb_n, gu = gu_n; const f32x4 pv4 = pv_n;
;                     if (rr < 15) { gb_n = *(const u32x4*)(Z + (size_t)(r + 1) * INP + 768 + c0); gu_n = *(const u32x4*)(Z + (size_t)(r + 1) * INP + 1280 + c0);
;                                    pv_n = *(const f32x4*)(pl + (size_t)(r + 1) * PLE + lane * 4); }
;                     float cv[8], uu[8]; float ss = 0.f;
; #pragma unroll
;                     for (int i = 0; i < 4; ++i) {
;                         uu[2 * i] = bf_lo(gu[i]); uu[2 * i + 1] = bf_hi(gu[i]);
;                         cv[2 * i] = bf_lo(gb[i]) * (w0[2 * i] * uu[2 * i] + w1[2 * i] * u1[2 * i] + w2[2 * i] * u2[2 * i]);
;                         cv[2 * i + 1] = bf_hi(gb[i]) * (w0[2 * i + 1] * uu[2 * i + 1] + w1[2 * i + 1] * u1[2 * i + 1] + w2[2 * i + 1] * u2[2 * i + 1]);
;                     }
; #pragma unroll
;                     for (int i = 0; i < 8; ++i) { ss += cv[i] * cv[i]; u2[i] = u1[i]; u1[i] = uu[i]; }
;                     ss = wave_sum(ss);
;                     const float rc = rsqrtf(ss * (1.0f / 512.0f) + EPS);
;                     u32x4 oc;
; #pragma unroll
	v_lshlrev_b32_e32 v188, 16, v30
	v_and_b32_e32 v189, 0xffff0000, v30
	v_lshlrev_b32_e32 v190, 16, v31
	v_and_b32_e32 v191, 0xffff0000, v31
	v_lshlrev_b32_e32 v192, 16, v32
	v_and_b32_e32 v193, 0xffff0000, v32
	v_lshlrev_b32_e32 v194, 16, v33
	v_and_b32_e32 v195, 0xffff0000, v33
	v_mul_f32_e32 v140, v164, v188
	v_mul_f32_e32 v141, v165, v189
	v_mul_f32_e32 v142, v166, v190
	v_mul_f32_e32 v143, v167, v191
	v_mul_f32_e32 v144, v168, v192
	v_mul_f32_e32 v145, v169, v193
	v_mul_f32_e32 v146, v170, v194
	v_mul_f32_e32 v147, v171, v195
	v_fmac_f32_e32 v140, v172, v204
	v_fmac_f32_e32 v141, v173, v205
	v_fmac_f32_e32 v142, v174, v206
	v_fmac_f32_e32 v143, v175, v207
	v_fmac_f32_e32 v144, v176, v208
	v_fmac_f32_e32 v145, v177, v209
	v_fmac_f32_e32 v146, v178, v210
	v_fmac_f32_e32 v147, v179, v211
	v_fmac_f32_e32 v140, v180, v196
	v_fmac_f32_e32 v141, v181, v197
	v_fmac_f32_e32 v142, v182, v198
	v_fmac_f32_e32 v143, v183, v199
	v_fmac_f32_e32 v144, v184, v200
	v_fmac_f32_e32 v145, v185, v201
	v_fmac_f32_e32 v146, v186, v202
	v_fmac_f32_e32 v147, v187, v203
	v_lshlrev_b32_e32 v150, 16, v14
	v_and_b32_e32 v151, 0xffff0000, v14
	v_mul_f32_e32 v140, v150, v140
	v_mul_f32_e32 v141, v151, v141
	v_lshlrev_b32_e32 v150, 16, v15
	v_and_b32_e32 v151, 0xffff0000, v15
	v_mul_f32_e32 v142, v150, v142
	v_mul_f32_e32 v143, v151, v143
	v_lshlrev_b32_e32 v150, 16, v16
	v_and_b32_e32 v151, 0xffff0000, v16
	v_mul_f32_e32 v144, v150, v144
	v_mul_f32_e32 v145, v151, v145
	v_lshlrev_b32_e32 v150, 16, v17
	v_and_b32_e32 v151, 0xffff0000, v17
	v_mul_f32_e32 v146, v150, v146
	v_mul_f32_e32 v147, v151, v147
	v_mul_f32_e32 v148, v140, v140
	v_fmac_f32_e32 v148, v141, v141
	v_fmac_f32_e32 v148, v142, v142
	v_fmac_f32_e32 v148, v143, v143
	v_fmac_f32_e32 v148, v144, v144
	v_fmac_f32_e32 v148, v145, v145
	v_fmac_f32_e32 v148, v146, v146
	v_fmac_f32_e32 v148, v147, v147
	v_mad_i64_i32 v[152:153], vcc, s41, v221, v[58:59]
	s_add_u32 s41, s41, 1
	global_load_dwordx4 v[14:17], v[152:153], off offset:1536
	global_load_dwordx4 v[30:33], v[152:153], off offset:2560
	ds_bpermute_b32 v150, v80, v148
	s_waitcnt lgkmcnt(0)
	v_add_f32_e32 v148, v148, v150
	ds_bpermute_b32 v150, v81, v148
	s_waitcnt lgkmcnt(0)
	v_add_f32_e32 v148, v148, v150
	ds_bpermute_b32 v150, v82, v148
	s_waitcnt lgkmcnt(0)
	v_add_f32_e32 v148, v148, v150
	ds_bpermute_b32 v150, v83, v148
	s_waitcnt lgkmcnt(0)
	v_add_f32_e32 v148, v148, v150
	ds_bpermute_b32 v150, v84, v148
	s_waitcnt lgkmcnt(0)
	v_add_f32_e32 v148, v148, v150
	ds_bpermute_b32 v150, v85, v148
	s_waitcnt lgkmcnt(0)
	v_add_f32_e32 v148, v148, v150
	v_fmamk_f32 v148, v148, 0x3b000000, v162
	v_mul_f32_e32 v150, 0x4b800000, v148
	v_cmp_gt_f32_e32 vcc, s31, v148
	s_nop 1
	v_cndmask_b32_e32 v148, v148, v150, vcc
	v_rsq_f32_e32 v148, v148
	s_nop 0
	v_mul_f32_e32 v150, 0x45800000, v148
	v_cndmask_b32_e32 v149, v148, v150, vcc
	v_mul_f32_e32 v140, v149, v140
	v_mul_f32_e32 v141, v149, v141
	v_mul_f32_e32 v142, v149, v142
	v_mul_f32_e32 v143, v149, v143
	v_mul_f32_e32 v144, v149, v144
	v_mul_f32_e32 v145, v149, v145
	v_mul_f32_e32 v146, v149, v146
	v_mul_f32_e32 v147, v149, v147
	v_cvt_pk_bf16_f32 v140, v140, v141
	v_cvt_pk_bf16_f32 v141, v142, v143
	v_cvt_pk_bf16_f32 v142, v144, v145
	v_cvt_pk_bf16_f32 v143, v146, v147
	global_store_dwordx4 v[156:157], v[140:143], off offset:2048
	v_lshl_add_u64 v[156:157], v[156:157], 0, s[20:21]
	s_waitcnt vmcnt(10)
	v_lshlrev_b32_e32 v196, 16, v18
	v_and_b32_e32 v197, 0xffff0000, v18
	v_lshlrev_b32_e32 v198, 16, v19
	v_and_b32_e32 v199, 0xffff0000, v19
	v_lshlrev_b32_e32 v200, 16, v20
	v_and_b32_e32 v201, 0xffff0000, v20
	v_lshlrev_b32_e32 v202, 16, v21
	v_and_b32_e32 v203, 0xffff0000, v21
	v_mul_f32_e32 v140, v164, v196
	v_mul_f32_e32 v141, v165, v197
	v_mul_f32_e32 v142, v166, v198
	v_mul_f32_e32 v143, v167, v199
	v_mul_f32_e32 v144, v168, v200
	v_mul_f32_e32 v145, v169, v201
	v_mul_f32_e32 v146, v170, v202
	v_mul_f32_e32 v147, v171, v203
	v_fmac_f32_e32 v140, v172, v188
	v_fmac_f32_e32 v141, v173, v189
	v_fmac_f32_e32 v142, v174, v190
	v_fmac_f32_e32 v143, v175, v191
	v_fmac_f32_e32 v144, v176, v192
	v_fmac_f32_e32 v145, v177, v193
	v_fmac_f32_e32 v146, v178, v194
	v_fmac_f32_e32 v147, v179, v195
	v_fmac_f32_e32 v140, v180, v204
	v_fmac_f32_e32 v141, v181, v205
	v_fmac_f32_e32 v142, v182, v206
	v_fmac_f32_e32 v143, v183, v207
	v_fmac_f32_e32 v144, v184, v208
	v_fmac_f32_e32 v145, v185, v209
	v_fmac_f32_e32 v146, v186, v210
	v_fmac_f32_e32 v147, v187, v211
	v_lshlrev_b32_e32 v150, 16, v2
	v_and_b32_e32 v151, 0xffff0000, v2
	v_mul_f32_e32 v140, v150, v140
	v_mul_f32_e32 v141, v151, v141
	v_lshlrev_b32_e32 v150, 16, v3
	v_and_b32_e32 v151, 0xffff0000, v3
	v_mul_f32_e32 v142, v150, v142
	v_mul_f32_e32 v143, v151, v143
	v_lshlrev_b32_e32 v150, 16, v4
	v_and_b32_e32 v151, 0xffff0000, v4
	v_mul_f32_e32 v144, v150, v144
	v_mul_f32_e32 v145, v151, v145
	v_lshlrev_b32_e32 v150, 16, v5
	v_and_b32_e32 v151, 0xffff0000, v5
	v_mul_f32_e32 v146, v150, v146
	v_mul_f32_e32 v147, v151, v147
	v_mul_f32_e32 v148, v140, v140
	v_fmac_f32_e32 v148, v141, v141
	v_fmac_f32_e32 v148, v142, v142
	v_fmac_f32_e32 v148, v143, v143
	v_fmac_f32_e32 v148, v144, v144
	v_fmac_f32_e32 v148, v145, v145
	v_fmac_f32_e32 v148, v146, v146
	v_fmac_f32_e32 v148, v147, v147
	v_mad_i64_i32 v[152:153], vcc, s41, v221, v[58:59]
	s_add_u32 s41, s41, 1
	global_load_dwordx4 v[2:5], v[152:153], off offset:1536
	global_load_dwordx4 v[18:21], v[152:153], off offset:2560
	ds_bpermute_b32 v150, v80, v148
	s_waitcnt lgkmcnt(0)
	v_add_f32_e32 v148, v148, v150
	ds_bpermute_b32 v150, v81, v148
	s_waitcnt lgkmcnt(0)
	v_add_f32_e32 v148, v148, v150
	ds_bpermute_b32 v150, v82, v148
	s_waitcnt lgkmcnt(0)
; __device__ __forceinline__ unsigned cvt_pk_bf16(float lo, float hi) { unsigned r; asm volatile("v_cvt_pk_bf16_f32 %0, %1, %2" : "=v"(r) : "v"(lo), "v"(hi)); return r; }
; __device__ __forceinline__ float bf_lo(unsigned w) { return __uint_as_float(w << 16); }
; __device__ __forceinline__ float bf_hi(unsigned w) { return __uint_as_float(w & 0xffff0000u); }
; __global__ void __launch_bounds__(512, 2) trunk_fwd(Args args) {
;     ...
;                 for (int rr = 0; rr < 16; ++rr) {
;                     const int r = r0 + rr;
;                     const u32x4 gb = gb_n, gu = gu_n; const f32x4 pv4 = pv_n;
;                     if (rr < 15) { gb_n = *(const u32x4*)(Z + (size_t)(r + 1) * INP + 768 + c0); gu_n = *(const u32x4*)(Z + (size_t)(r + 1) * INP + 1280 + c0);
;                                    pv_n = *(const f32x4*)(pl + (size_t)(r + 1) * PLE + lane * 4); }
;                     float cv[8], uu[8]; float ss = 0.f;
; #pragma unroll
;                     for (int i = 0; i < 4; ++i) {
;                         uu[2 * i] = bf_lo(gu[i]); uu[2 * i + 1] = bf_hi(gu[i]);
;                         cv[2 * i] = bf_lo(gb[i]) * (w0[2 * i] * uu[2 * i] + w1[2 * i] * u1[2 * i] + w2[2 * i] * u2[2 * i]);
;                         cv[2 * i + 1] = bf_hi(gb[i]) * (w0[2 * i + 1] * uu[2 * i + 1] + w1[2 * i + 1] * u1[2 * i + 1] + w2[2 * i + 1] * u2[2 * i + 1]);
;                     }
; #pragma unroll
;                     for (int i = 0; i < 8; ++i) { ss += cv[i] * cv[i]; u2[i] = u1[i]; u1[i] = uu[i]; }
;                     ss = wave_sum(ss);
;                     const float rc = rsqrtf(ss * (1.0f / 512.0f) + EPS);
;                     u32x4 oc;
; #pragma unroll
;                     for (int i = 0; i < 4; ++i) oc[i] = cvt_pk_bf16(cv[2 * i] * rc, cv[2 * i + 1] * rc);
;                     *(u32x4*)(MIX + (size_t)r * 1024 + 512 + c0) = oc;
;                     u32x2 pw; pw.x = cvt_pk_bf16(pv4[0], pv4[1]); pw.y = cvt_pk_bf16(pv4[2], pv4[3]);
;                     *(u32x2*)(PB + (size_t)r * PLE + lane * 4) = pw;
	v_add_f32_e32 v148, v148, v150
	ds_bpermute_b32 v150, v83, v148
	s_waitcnt lgkmcnt(0)
	v_add_f32_e32 v148, v148, v150
	ds_bpermute_b32 v150, v84, v148
	s_waitcnt lgkmcnt(0)
	v_add_f32_e32 v148, v148, v150
	ds_bpermute_b32 v150, v85, v148
	s_waitcnt lgkmcnt(0)
	v_add_f32_e32 v148, v148, v150
	v_fmamk_f32 v148, v148, 0x3b000000, v162
	v_mul_f32_e32 v150, 0x4b800000, v148
	v_cmp_gt_f32_e32 vcc, s31, v148
	s_nop 1
	v_cndmask_b32_e32 v148, v148, v150, vcc
	v_rsq_f32_e32 v148, v148
	s_nop 0
	v_mul_f32_e32 v150, 0x45800000, v148
	v_cndmask_b32_e32 v149, v148, v150, vcc
	v_mul_f32_e32 v140, v149, v140
	v_mul_f32_e32 v141, v149, v141
	v_mul_f32_e32 v142, v149, v142
	v_mul_f32_e32 v143, v149, v143
	v_mul_f32_e32 v144, v149, v144
	v_mul_f32_e32 v145, v149, v145
	v_mul_f32_e32 v146, v149, v146
	v_mul_f32_e32 v147, v149, v147
	v_cvt_pk_bf16_f32 v140, v140, v141
	v_cvt_pk_bf16_f32 v141, v142, v143
	v_cvt_pk_bf16_f32 v142, v144, v145
	v_cvt_pk_bf16_f32 v143, v146, v147
	global_store_dwordx4 v[156:157], v[140:143], off
	s_waitcnt vmcnt(10)
	v_lshlrev_b32_e32 v204, 16, v22
	v_and_b32_e32 v205, 0xffff0000, v22
	v_lshlrev_b32_e32 v206, 16, v23
	v_and_b32_e32 v207, 0xffff0000, v23
	v_lshlrev_b32_e32 v208, 16, v24
	v_and_b32_e32 v209, 0xffff0000, v24
	v_lshlrev_b32_e32 v210, 16, v25
	v_and_b32_e32 v211, 0xffff0000, v25
	v_mul_f32_e32 v140, v164, v204
	v_mul_f32_e32 v141, v165, v205
	v_mul_f32_e32 v142, v166, v206
	v_mul_f32_e32 v143, v167, v207
	v_mul_f32_e32 v144, v168, v208
	v_mul_f32_e32 v145, v169, v209
	v_mul_f32_e32 v146, v170, v210
	v_mul_f32_e32 v147, v171, v211
	v_fmac_f32_e32 v140, v172, v196
	v_fmac_f32_e32 v141, v173, v197
	v_fmac_f32_e32 v142, v174, v198
	v_fmac_f32_e32 v143, v175, v199
	v_fmac_f32_e32 v144, v176, v200
	v_fmac_f32_e32 v145, v177, v201
	v_fmac_f32_e32 v146, v178, v202
	v_fmac_f32_e32 v147, v179, v203
	v_fmac_f32_e32 v140, v180, v188
	v_fmac_f32_e32 v141, v181, v189
	v_fmac_f32_e32 v142, v182, v190
	v_fmac_f32_e32 v143, v183, v191
	v_fmac_f32_e32 v144, v184, v192
	v_fmac_f32_e32 v145, v185, v193
	v_fmac_f32_e32 v146, v186, v194
	v_fmac_f32_e32 v147, v187, v195
	v_lshlrev_b32_e32 v150, 16, v6
	v_and_b32_e32 v151, 0xffff0000, v6
	v_mul_f32_e32 v140, v150, v140
	v_mul_f32_e32 v141, v151, v141
	v_lshlrev_b32_e32 v150, 16, v7
	v_and_b32_e32 v151, 0xffff0000, v7
	v_mul_f32_e32 v142, v150, v142
	v_mul_f32_e32 v143, v151, v143
	v_lshlrev_b32_e32 v150, 16, v8
	v_and_b32_e32 v151, 0xffff0000, v8
	v_mul_f32_e32 v144, v150, v144
	v_mul_f32_e32 v145, v151, v145
	v_lshlrev_b32_e32 v150, 16, v9
	v_and_b32_e32 v151, 0xffff0000, v9
	v_mul_f32_e32 v146, v150, v146
	v_mul_f32_e32 v147, v151, v147
	v_mul_f32_e32 v148, v140, v140
	v_fmac_f32_e32 v148, v141, v141
	v_fmac_f32_e32 v148, v142, v142
	v_fmac_f32_e32 v148, v143, v143
	v_fmac_f32_e32 v148, v144, v144
	v_fmac_f32_e32 v148, v145, v145
	v_fmac_f32_e32 v148, v146, v146
	v_fmac_f32_e32 v148, v147, v147
	v_mad_i64_i32 v[152:153], vcc, s41, v221, v[58:59]
	s_add_u32 s41, s41, 1
	global_load_dwordx4 v[6:9], v[152:153], off offset:1536
	global_load_dwordx4 v[22:25], v[152:153], off offset:2560
	ds_bpermute_b32 v150, v80, v148
	s_waitcnt lgkmcnt(0)
	v_add_f32_e32 v148, v148, v150
	ds_bpermute_b32 v150, v81, v148
	s_waitcnt lgkmcnt(0)
	v_add_f32_e32 v148, v148, v150
	ds_bpermute_b32 v150, v82, v148
	s_waitcnt lgkmcnt(0)
	v_add_f32_e32 v148, v148, v150
	ds_bpermute_b32 v150, v83, v148
	s_waitcnt lgkmcnt(0)
	v_add_f32_e32 v148, v148, v150
	ds_bpermute_b32 v150, v84, v148
	s_waitcnt lgkmcnt(0)
	v_add_f32_e32 v148, v148, v150
	ds_bpermute_b32 v150, v85, v148
	s_waitcnt lgkmcnt(0)
	v_add_f32_e32 v148, v148, v150
	v_fmamk_f32 v148, v148, 0x3b000000, v162
	v_mul_f32_e32 v150, 0x4b800000, v148
	v_cmp_gt_f32_e32 vcc, s31, v148
	s_nop 1
	v_cndmask_b32_e32 v148, v148, v150, vcc
	v_rsq_f32_e32 v148, v148
	s_nop 0
	v_mul_f32_e32 v150, 0x45800000, v148
	v_cndmask_b32_e32 v149, v148, v150, vcc
	v_mul_f32_e32 v140, v149, v140
	v_mul_f32_e32 v141, v149, v141
	v_mul_f32_e32 v142, v149, v142
	v_mul_f32_e32 v143, v149, v143
	v_mul_f32_e32 v144, v149, v144
	v_mul_f32_e32 v145, v149, v145
	v_mul_f32_e32 v146, v149, v146
	v_mul_f32_e32 v147, v149, v147
	v_cvt_pk_bf16_f32 v140, v140, v141
	v_cvt_pk_bf16_f32 v141, v142, v143
	v_cvt_pk_bf16_f32 v142, v144, v145
	v_cvt_pk_bf16_f32 v143, v146, v147
	global_store_dwordx4 v[156:157], v[140:143], off offset:2048
	v_lshl_add_u64 v[156:157], v[156:157], 0, s[20:21]
	s_waitcnt vmcnt(10)
	v_lshlrev_b32_e32 v188, 16, v26
	v_and_b32_e32 v189, 0xffff0000, v26
	v_lshlrev_b32_e32 v190, 16, v27
	v_and_b32_e32 v191, 0xffff0000, v27
	v_lshlrev_b32_e32 v192, 16, v28
	v_and_b32_e32 v193, 0xffff0000, v28
	v_lshlrev_b32_e32 v194, 16, v29
	v_and_b32_e32 v195, 0xffff0000, v29
	v_mul_f32_e32 v140, v164, v188
	v_mul_f32_e32 v141, v165, v189
	v_mul_f32_e32 v142, v166, v190
	v_mul_f32_e32 v143, v167, v191
	v_mul_f32_e32 v144, v168, v192
	v_mul_f32_e32 v145, v169, v193
	v_mul_f32_e32 v146, v170, v194
	v_mul_f32_e32 v147, v171, v195
	v_fmac_f32_e32 v140, v172, v204
	v_fmac_f32_e32 v141, v173, v205
	v_fmac_f32_e32 v142, v174, v206
	v_fmac_f32_e32 v143, v175, v207
	v_fmac_f32_e32 v144, v176, v208
	v_fmac_f32_e32 v145, v177, v209
	v_fmac_f32_e32 v146, v178, v210
	v_fmac_f32_e32 v147, v179, v211
	v_fmac_f32_e32 v140, v180, v196
	v_fmac_f32_e32 v141, v181, v197
	v_fmac_f32_e32 v142, v182, v198
	v_fmac_f32_e32 v143, v183, v199
	v_fmac_f32_e32 v144, v184, v200
	v_fmac_f32_e32 v145, v185, v201
	v_fmac_f32_e32 v146, v186, v202
	v_fmac_f32_e32 v147, v187, v203
	v_lshlrev_b32_e32 v150, 16, v10
	v_and_b32_e32 v151, 0xffff0000, v10
	v_mul_f32_e32 v140, v150, v140
	v_mul_f32_e32 v141, v151, v141
	v_lshlrev_b32_e32 v150, 16, v11
	v_and_b32_e32 v151, 0xffff0000, v11
	v_mul_f32_e32 v142, v150, v142
	v_mul_f32_e32 v143, v151, v143
	v_lshlrev_b32_e32 v150, 16, v12
	v_and_b32_e32 v151, 0xffff0000, v12
	v_mul_f32_e32 v144, v150, v144
	v_mul_f32_e32 v145, v151, v145
	v_lshlrev_b32_e32 v150, 16, v13
	v_and_b32_e32 v151, 0xffff0000, v13
	v_mul_f32_e32 v146, v150, v146
	v_mul_f32_e32 v147, v151, v147
	v_mul_f32_e32 v148, v140, v140
	v_fmac_f32_e32 v148, v141, v141
	v_fmac_f32_e32 v148, v142, v142
	v_fmac_f32_e32 v148, v143, v143
	v_fmac_f32_e32 v148, v144, v144
	v_fmac_f32_e32 v148, v145, v145
	v_fmac_f32_e32 v148, v146, v146
	v_fmac_f32_e32 v148, v147, v147
	v_mad_i64_i32 v[152:153], vcc, s41, v221, v[58:59]
	s_add_u32 s41, s41, 1
	global_load_dwordx4 v[10:13], v[152:153], off offset:1536
	global_load_dwordx4 v[26:29], v[152:153], off offset:2560
	ds_bpermute_b32 v150, v80, v148
	s_waitcnt lgkmcnt(0)
; __device__ __forceinline__ unsigned cvt_pk_bf16(float lo, float hi) { unsigned r; asm volatile("v_cvt_pk_bf16_f32 %0, %1, %2" : "=v"(r) : "v"(lo), "v"(hi)); return r; }
; __device__ __forceinline__ float bf_lo(unsigned w) { return __uint_as_float(w << 16); }
; __device__ __forceinline__ float bf_hi(unsigned w) { return __uint_as_float(w & 0xffff0000u); }
; __global__ void __launch_bounds__(512, 2) trunk_fwd(Args args) {
;     ...
;                 for (int rr = 0; rr < 16; ++rr) {
;                     const int r = r0 + rr;
;                     const u32x4 gb = gb_n, gu = gu_n; const f32x4 pv4 = pv_n;
;                     if (rr < 15) { gb_n = *(const u32x4*)(Z + (size_t)(r + 1) * INP + 768 + c0); gu_n = *(const u32x4*)(Z + (size_t)(r + 1) * INP + 1280 + c0);
;                                    pv_n = *(const f32x4*)(pl + (size_t)(r + 1) * PLE + lane * 4); }
;                     float cv[8], uu[8]; float ss = 0.f;
; #pragma unroll
;                     for (int i = 0; i < 4; ++i) {
;                         uu[2 * i] = bf_lo(gu[i]); uu[2 * i + 1] = bf_hi(gu[i]);
;                         cv[2 * i] = bf_lo(gb[i]) * (w0[2 * i] * uu[2 * i] + w1[2 * i] * u1[2 * i] + w2[2 * i] * u2[2 * i]);
;                         cv[2 * i + 1] = bf_hi(gb[i]) * (w0[2 * i + 1] * uu[2 * i + 1] + w1[2 * i + 1] * u1[2 * i + 1] + w2[2 * i + 1] * u2[2 * i + 1]);
;                     }
; #pragma unroll
;                     for (int i = 0; i < 8; ++i) { ss += cv[i] * cv[i]; u2[i] = u1[i]; u1[i] = uu[i]; }
;                     ss = wave_sum(ss);
;                     const float rc = rsqrtf(ss * (1.0f / 512.0f) + EPS);
;                     u32x4 oc;
; #pragma unroll
;                     for (int i = 0; i < 4; ++i) oc[i] = cvt_pk_bf16(cv[2 * i] * rc, cv[2 * i + 1] * rc);
;                     *(u32x4*)(MIX + (size_t)r * 1024 + 512 + c0) = oc;
;                     u32x2 pw; pw.x = cvt_pk_bf16(pv4[0], pv4[1]); pw.y = cvt_pk_bf16(pv4[2], pv4[3]);
;                     *(u32x2*)(PB + (size_t)r * PLE + lane * 4) = pw;
	v_add_f32_e32 v148, v148, v150
	ds_bpermute_b32 v150, v81, v148
	s_waitcnt lgkmcnt(0)
	v_add_f32_e32 v148, v148, v150
	ds_bpermute_b32 v150, v82, v148
	s_waitcnt lgkmcnt(0)
	v_add_f32_e32 v148, v148, v150
	ds_bpermute_b32 v150, v83, v148
	s_waitcnt lgkmcnt(0)
	v_add_f32_e32 v148, v148, v150
	ds_bpermute_b32 v150, v84, v148
	s_waitcnt lgkmcnt(0)
	v_add_f32_e32 v148, v148, v150
	ds_bpermute_b32 v150, v85, v148
	s_waitcnt lgkmcnt(0)
	v_add_f32_e32 v148, v148, v150
	v_fmamk_f32 v148, v148, 0x3b000000, v162
	v_mul_f32_e32 v150, 0x4b800000, v148
	v_cmp_gt_f32_e32 vcc, s31, v148
	s_nop 1
	v_cndmask_b32_e32 v148, v148, v150, vcc
	v_rsq_f32_e32 v148, v148
	s_nop 0
	v_mul_f32_e32 v150, 0x45800000, v148
	v_cndmask_b32_e32 v149, v148, v150, vcc
	v_mul_f32_e32 v140, v149, v140
	v_mul_f32_e32 v141, v149, v141
	v_mul_f32_e32 v142, v149, v142
	v_mul_f32_e32 v143, v149, v143
	v_mul_f32_e32 v144, v149, v144
	v_mul_f32_e32 v145, v149, v145
	v_mul_f32_e32 v146, v149, v146
	v_mul_f32_e32 v147, v149, v147
	v_cvt_pk_bf16_f32 v140, v140, v141
	v_cvt_pk_bf16_f32 v141, v142, v143
	v_cvt_pk_bf16_f32 v142, v144, v145
	v_cvt_pk_bf16_f32 v143, v146, v147
	global_store_dwordx4 v[156:157], v[140:143], off
	s_waitcnt vmcnt(10)
	v_lshlrev_b32_e32 v196, 16, v30
	v_and_b32_e32 v197, 0xffff0000, v30
	v_lshlrev_b32_e32 v198, 16, v31
	v_and_b32_e32 v199, 0xffff0000, v31
	v_lshlrev_b32_e32 v200, 16, v32
	v_and_b32_e32 v201, 0xffff0000, v32
	v_lshlrev_b32_e32 v202, 16, v33
	v_and_b32_e32 v203, 0xffff0000, v33
	v_mul_f32_e32 v140, v164, v196
	v_mul_f32_e32 v141, v165, v197
	v_mul_f32_e32 v142, v166, v198
	v_mul_f32_e32 v143, v167, v199
	v_mul_f32_e32 v144, v168, v200
	v_mul_f32_e32 v145, v169, v201
	v_mul_f32_e32 v146, v170, v202
	v_mul_f32_e32 v147, v171, v203
	v_fmac_f32_e32 v140, v172, v188
	v_fmac_f32_e32 v141, v173, v189
	v_fmac_f32_e32 v142, v174, v190
	v_fmac_f32_e32 v143, v175, v191
	v_fmac_f32_e32 v144, v176, v192
	v_fmac_f32_e32 v145, v177, v193
	v_fmac_f32_e32 v146, v178, v194
	v_fmac_f32_e32 v147, v179, v195
	v_fmac_f32_e32 v140, v180, v204
	v_fmac_f32_e32 v141, v181, v205
	v_fmac_f32_e32 v142, v182, v206
	v_fmac_f32_e32 v143, v183, v207
	v_fmac_f32_e32 v144, v184, v208
	v_fmac_f32_e32 v145, v185, v209
	v_fmac_f32_e32 v146, v186, v210
	v_fmac_f32_e32 v147, v187, v211
	v_lshlrev_b32_e32 v150, 16, v14
	v_and_b32_e32 v151, 0xffff0000, v14
	v_mul_f32_e32 v140, v150, v140
	v_mul_f32_e32 v141, v151, v141
	v_lshlrev_b32_e32 v150, 16, v15
	v_and_b32_e32 v151, 0xffff0000, v15
	v_mul_f32_e32 v142, v150, v142
	v_mul_f32_e32 v143, v151, v143
	v_lshlrev_b32_e32 v150, 16, v16
	v_and_b32_e32 v151, 0xffff0000, v16
	v_mul_f32_e32 v144, v150, v144
	v_mul_f32_e32 v145, v151, v145
	v_lshlrev_b32_e32 v150, 16, v17
	v_and_b32_e32 v151, 0xffff0000, v17
	v_mul_f32_e32 v146, v150, v146
	v_mul_f32_e32 v147, v151, v147
	v_mul_f32_e32 v148, v140, v140
	v_fmac_f32_e32 v148, v141, v141
	v_fmac_f32_e32 v148, v142, v142
	v_fmac_f32_e32 v148, v143, v143
	v_fmac_f32_e32 v148, v144, v144
	v_fmac_f32_e32 v148, v145, v145
	v_fmac_f32_e32 v148, v146, v146
	v_fmac_f32_e32 v148, v147, v147
	v_mad_i64_i32 v[152:153], vcc, s41, v221, v[58:59]
	s_add_u32 s41, s41, 1
	global_load_dwordx4 v[14:17], v[152:153], off offset:1536
	global_load_dwordx4 v[30:33], v[152:153], off offset:2560
	ds_bpermute_b32 v150, v80, v148
	s_waitcnt lgkmcnt(0)
	v_add_f32_e32 v148, v148, v150
	ds_bpermute_b32 v150, v81, v148
	s_waitcnt lgkmcnt(0)
	v_add_f32_e32 v148, v148, v150
	ds_bpermute_b32 v150, v82, v148
	s_waitcnt lgkmcnt(0)
	v_add_f32_e32 v148, v148, v150
	ds_bpermute_b32 v150, v83, v148
	s_waitcnt lgkmcnt(0)
	v_add_f32_e32 v148, v148, v150
	ds_bpermute_b32 v150, v84, v148
	s_waitcnt lgkmcnt(0)
	v_add_f32_e32 v148, v148, v150
	ds_bpermute_b32 v150, v85, v148
	s_waitcnt lgkmcnt(0)
	v_add_f32_e32 v148, v148, v150
	v_fmamk_f32 v148, v148, 0x3b000000, v162
	v_mul_f32_e32 v150, 0x4b800000, v148
	v_cmp_gt_f32_e32 vcc, s31, v148
	s_nop 1
	v_cndmask_b32_e32 v148, v148, v150, vcc
	v_rsq_f32_e32 v148, v148
	s_nop 0
	v_mul_f32_e32 v150, 0x45800000, v148
	v_cndmask_b32_e32 v149, v148, v150, vcc
	v_mul_f32_e32 v140, v149, v140
	v_mul_f32_e32 v141, v149, v141
	v_mul_f32_e32 v142, v149, v142
	v_mul_f32_e32 v143, v149, v143
	v_mul_f32_e32 v144, v149, v144
	v_mul_f32_e32 v145, v149, v145
	v_mul_f32_e32 v146, v149, v146
	v_mul_f32_e32 v147, v149, v147
	v_cvt_pk_bf16_f32 v140, v140, v141
	v_cvt_pk_bf16_f32 v141, v142, v143
	v_cvt_pk_bf16_f32 v142, v144, v145
	v_cvt_pk_bf16_f32 v143, v146, v147
	global_store_dwordx4 v[156:157], v[140:143], off offset:2048
	v_lshl_add_u64 v[156:157], v[156:157], 0, s[20:21]
	s_waitcnt vmcnt(10)
; __device__ __forceinline__ unsigned cvt_pk_bf16(float lo, float hi) { unsigned r; asm volatile("v_cvt_pk_bf16_f32 %0, %1, %2" : "=v"(r) : "v"(lo), "v"(hi)); return r; }
; __device__ __forceinline__ float bf_lo(unsigned w) { return __uint_as_float(w << 16); }
; __device__ __forceinline__ float bf_hi(unsigned w) { return __uint_as_float(w & 0xffff0000u); }
; __global__ void __launch_bounds__(512, 2) trunk_fwd(Args args) {
;     ...
;                 for (int rr = 0; rr < 16; ++rr) {
;                     const int r = r0 + rr;
;                     const u32x4 gb = gb_n, gu = gu_n; const f32x4 pv4 = pv_n;
;                     if (rr < 15) { gb_n = *(const u32x4*)(Z + (size_t)(r + 1) * INP + 768 + c0); gu_n = *(const u32x4*)(Z + (size_t)(r + 1) * INP + 1280 + c0);
;                                    pv_n = *(const f32x4*)(pl + (size_t)(r + 1) * PLE + lane * 4); }
;                     float cv[8], uu[8]; float ss = 0.f;
; #pragma unroll
;                     for (int i = 0; i < 4; ++i) {
;                         uu[2 * i] = bf_lo(gu[i]); uu[2 * i + 1] = bf_hi(gu[i]);
;                         cv[2 * i] = bf_lo(gb[i]) * (w0[2 * i] * uu[2 * i] + w1[2 * i] * u1[2 * i] + w2[2 * i] * u2[2 * i]);
;                         cv[2 * i + 1] = bf_hi(gb[i]) * (w0[2 * i + 1] * uu[2 * i + 1] + w1[2 * i + 1] * u1[2 * i + 1] + w2[2 * i + 1] * u2[2 * i + 1]);
;                     }
; #pragma unroll
;                     for (int i = 0; i < 8; ++i) { ss += cv[i] * cv[i]; u2[i] = u1[i]; u1[i] = uu[i]; }
;                     ss = wave_sum(ss);
;                     const float rc = rsqrtf(ss * (1.0f / 512.0f) + EPS);
;                     u32x4 oc;
; #pragma unroll
;                     for (int i = 0; i < 4; ++i) oc[i] = cvt_pk_bf16(cv[2 * i] * rc, cv[2 * i + 1] * rc);
;                     *(u32x4*)(MIX + (size_t)r * 1024 + 512 + c0) = oc;
;                     u32x2 pw; pw.x = cvt_pk_bf16(pv4[0], pv4[1]); pw.y = cvt_pk_bf16(pv4[2], pv4[3]);
;                     *(u32x2*)(PB + (size_t)r * PLE + lane * 4) = pw;
	v_lshlrev_b32_e32 v204, 16, v18
	v_and_b32_e32 v205, 0xffff0000, v18
	v_lshlrev_b32_e32 v206, 16, v19
	v_and_b32_e32 v207, 0xffff0000, v19
	v_lshlrev_b32_e32 v208, 16, v20
	v_and_b32_e32 v209, 0xffff0000, v20
	v_lshlrev_b32_e32 v210, 16, v21
	v_and_b32_e32 v211, 0xffff0000, v21
	v_mul_f32_e32 v140, v164, v204
	v_mul_f32_e32 v141, v165, v205
	v_mul_f32_e32 v142, v166, v206
	v_mul_f32_e32 v143, v167, v207
	v_mul_f32_e32 v144, v168, v208
	v_mul_f32_e32 v145, v169, v209
	v_mul_f32_e32 v146, v170, v210
	v_mul_f32_e32 v147, v171, v211
	v_fmac_f32_e32 v140, v172, v196
	v_fmac_f32_e32 v141, v173, v197
	v_fmac_f32_e32 v142, v174, v198
	v_fmac_f32_e32 v143, v175, v199
	v_fmac_f32_e32 v144, v176, v200
	v_fmac_f32_e32 v145, v177, v201
	v_fmac_f32_e32 v146, v178, v202
	v_fmac_f32_e32 v147, v179, v203
	v_fmac_f32_e32 v140, v180, v188
	v_fmac_f32_e32 v141, v181, v189
	v_fmac_f32_e32 v142, v182, v190
	v_fmac_f32_e32 v143, v183, v191
	v_fmac_f32_e32 v144, v184, v192
	v_fmac_f32_e32 v145, v185, v193
	v_fmac_f32_e32 v146, v186, v194
	v_fmac_f32_e32 v147, v187, v195
	v_lshlrev_b32_e32 v150, 16, v2
	v_and_b32_e32 v151, 0xffff0000, v2
	v_mul_f32_e32 v140, v150, v140
	v_mul_f32_e32 v141, v151, v141
	v_lshlrev_b32_e32 v150, 16, v3
	v_and_b32_e32 v151, 0xffff0000, v3
	v_mul_f32_e32 v142, v150, v142
	v_mul_f32_e32 v143, v151, v143
	v_lshlrev_b32_e32 v150, 16, v4
	v_and_b32_e32 v151, 0xffff0000, v4
	v_mul_f32_e32 v144, v150, v144
	v_mul_f32_e32 v145, v151, v145
	v_lshlrev_b32_e32 v150, 16, v5
	v_and_b32_e32 v151, 0xffff0000, v5
	v_mul_f32_e32 v146, v150, v146
	v_mul_f32_e32 v147, v151, v147
	v_mul_f32_e32 v148, v140, v140
	v_fmac_f32_e32 v148, v141, v141
	v_fmac_f32_e32 v148, v142, v142
	v_fmac_f32_e32 v148, v143, v143
	v_fmac_f32_e32 v148, v144, v144
	v_fmac_f32_e32 v148, v145, v145
	v_fmac_f32_e32 v148, v146, v146
	v_fmac_f32_e32 v148, v147, v147
	v_mad_i64_i32 v[152:153], vcc, s41, v221, v[58:59]
	s_add_u32 s41, s41, 1
	global_load_dwordx4 v[2:5], v[152:153], off offset:1536
	global_load_dwordx4 v[18:21], v[152:153], off offset:2560
	ds_bpermute_b32 v150, v80, v148
	s_waitcnt lgkmcnt(0)
	v_add_f32_e32 v148, v148, v150
	ds_bpermute_b32 v150, v81, v148
	s_waitcnt lgkmcnt(0)
	v_add_f32_e32 v148, v148, v150
	ds_bpermute_b32 v150, v82, v148
	s_waitcnt lgkmcnt(0)
	v_add_f32_e32 v148, v148, v150
	ds_bpermute_b32 v150, v83, v148
	s_waitcnt lgkmcnt(0)
	v_add_f32_e32 v148, v148, v150
	ds_bpermute_b32 v150, v84, v148
	s_waitcnt lgkmcnt(0)
	v_add_f32_e32 v148, v148, v150
	ds_bpermute_b32 v150, v85, v148
	s_waitcnt lgkmcnt(0)
	v_add_f32_e32 v148, v148, v150
	v_fmamk_f32 v148, v148, 0x3b000000, v162
	v_mul_f32_e32 v150, 0x4b800000, v148
	v_cmp_gt_f32_e32 vcc, s31, v148
	s_nop 1
	v_cndmask_b32_e32 v148, v148, v150, vcc
	v_rsq_f32_e32 v148, v148
	s_nop 0
	v_mul_f32_e32 v150, 0x45800000, v148
	v_cndmask_b32_e32 v149, v148, v150, vcc
	v_mul_f32_e32 v140, v149, v140
	v_mul_f32_e32 v141, v149, v141
	v_mul_f32_e32 v142, v149, v142
	v_mul_f32_e32 v143, v149, v143
	v_mul_f32_e32 v144, v149, v144
	v_mul_f32_e32 v145, v149, v145
	v_mul_f32_e32 v146, v149, v146
	v_mul_f32_e32 v147, v149, v147
	v_cvt_pk_bf16_f32 v140, v140, v141
	v_cvt_pk_bf16_f32 v141, v142, v143
	v_cvt_pk_bf16_f32 v142, v144, v145
	v_cvt_pk_bf16_f32 v143, v146, v147
	global_store_dwordx4 v[156:157], v[140:143], off
	s_waitcnt vmcnt(10)
	v_lshlrev_b32_e32 v188, 16, v22
	v_and_b32_e32 v189, 0xffff0000, v22
	v_lshlrev_b32_e32 v190, 16, v23
	v_and_b32_e32 v191, 0xffff0000, v23
	v_lshlrev_b32_e32 v192, 16, v24
	v_and_b32_e32 v193, 0xffff0000, v24
	v_lshlrev_b32_e32 v194, 16, v25
	v_and_b32_e32 v195, 0xffff0000, v25
	v_mul_f32_e32 v140, v164, v188
	v_mul_f32_e32 v141, v165, v189
	v_mul_f32_e32 v142, v166, v190
	v_mul_f32_e32 v143, v167, v191
	v_mul_f32_e32 v144, v168, v192
	v_mul_f32_e32 v145, v169, v193
	v_mul_f32_e32 v146, v170, v194
	v_mul_f32_e32 v147, v171, v195
	v_fmac_f32_e32 v140, v172, v204
	v_fmac_f32_e32 v141, v173, v205
	v_fmac_f32_e32 v142, v174, v206
	v_fmac_f32_e32 v143, v175, v207
	v_fmac_f32_e32 v144, v176, v208
	v_fmac_f32_e32 v145, v177, v209
	v_fmac_f32_e32 v146, v178, v210
	v_fmac_f32_e32 v147, v179, v211
	v_fmac_f32_e32 v140, v180, v196
	v_fmac_f32_e32 v141, v181, v197
	v_fmac_f32_e32 v142, v182, v198
	v_fmac_f32_e32 v143, v183, v199
	v_fmac_f32_e32 v144, v184, v200
	v_fmac_f32_e32 v145, v185, v201
	v_fmac_f32_e32 v146, v186, v202
	v_fmac_f32_e32 v147, v187, v203
	v_lshlrev_b32_e32 v150, 16, v6
	v_and_b32_e32 v151, 0xffff0000, v6
	v_mul_f32_e32 v140, v150, v140
	v_mul_f32_e32 v141, v151, v141
	v_lshlrev_b32_e32 v150, 16, v7
	v_and_b32_e32 v151, 0xffff0000, v7
	v_mul_f32_e32 v142, v150, v142
	v_mul_f32_e32 v143, v151, v143
	v_lshlrev_b32_e32 v150, 16, v8
	v_and_b32_e32 v151, 0xffff0000, v8
	v_mul_f32_e32 v144, v150, v144
	v_mul_f32_e32 v145, v151, v145
	v_lshlrev_b32_e32 v150, 16, v9
	v_and_b32_e32 v151, 0xffff0000, v9
	v_mul_f32_e32 v146, v150, v146
	v_mul_f32_e32 v147, v151, v147
	v_mul_f32_e32 v148, v140, v140
	v_fmac_f32_e32 v148, v141, v141
	v_fmac_f32_e32 v148, v142, v142
	v_fmac_f32_e32 v148, v143, v143
	v_fmac_f32_e32 v148, v144, v144
	v_fmac_f32_e32 v148, v145, v145
	v_fmac_f32_e32 v148, v146, v146
	v_fmac_f32_e32 v148, v147, v147
	v_mad_i64_i32 v[152:153], vcc, s41, v221, v[58:59]
	s_add_u32 s41, s41, 1
	global_load_dwordx4 v[6:9], v[152:153], off offset:1536
	global_load_dwordx4 v[22:25], v[152:153], off offset:2560
	ds_bpermute_b32 v150, v80, v148
	s_waitcnt lgkmcnt(0)
	v_add_f32_e32 v148, v148, v150
	ds_bpermute_b32 v150, v81, v148
	s_waitcnt lgkmcnt(0)
	v_add_f32_e32 v148, v148, v150
	ds_bpermute_b32 v150, v82, v148
	s_waitcnt lgkmcnt(0)
	v_add_f32_e32 v148, v148, v150
	ds_bpermute_b32 v150, v83, v148
	s_waitcnt lgkmcnt(0)
; __device__ __forceinline__ unsigned cvt_pk_bf16(float lo, float hi) { unsigned r; asm volatile("v_cvt_pk_bf16_f32 %0, %1, %2" : "=v"(r) : "v"(lo), "v"(hi)); return r; }
; __device__ __forceinline__ float bf_lo(unsigned w) { return __uint_as_float(w << 16); }
; __device__ __forceinline__ float bf_hi(unsigned w) { return __uint_as_float(w & 0xffff0000u); }
; __global__ void __launch_bounds__(512, 2) trunk_fwd(Args args) {
;     ...
;                 for (int rr = 0; rr < 16; ++rr) {
;                     const int r = r0 + rr;
;                     const u32x4 gb = gb_n, gu = gu_n; const f32x4 pv4 = pv_n;
;                     if (rr < 15) { gb_n = *(const u32x4*)(Z + (size_t)(r + 1) * INP + 768 + c0); gu_n = *(const u32x4*)(Z + (size_t)(r + 1) * INP + 1280 + c0);
;                                    pv_n = *(const f32x4*)(pl + (size_t)(r + 1) * PLE + lane * 4); }
;                     float cv[8], uu[8]; float ss = 0.f;
; #pragma unroll
;                     for (int i = 0; i < 4; ++i) {
;                         uu[2 * i] = bf_lo(gu[i]); uu[2 * i + 1] = bf_hi(gu[i]);
;                         cv[2 * i] = bf_lo(gb[i]) * (w0[2 * i] * uu[2 * i] + w1[2 * i] * u1[2 * i] + w2[2 * i] * u2[2 * i]);
;                         cv[2 * i + 1] = bf_hi(gb[i]) * (w0[2 * i + 1] * uu[2 * i + 1] + w1[2 * i + 1] * u1[2 * i + 1] + w2[2 * i + 1] * u2[2 * i + 1]);
;                     }
; #pragma unroll
;                     for (int i = 0; i < 8; ++i) { ss += cv[i] * cv[i]; u2[i] = u1[i]; u1[i] = uu[i]; }
;                     ss = wave_sum(ss);
;                     const float rc = rsqrtf(ss * (1.0f / 512.0f) + EPS);
;                     u32x4 oc;
; #pragma unroll
;                     for (int i = 0; i < 4; ++i) oc[i] = cvt_pk_bf16(cv[2 * i] * rc, cv[2 * i + 1] * rc);
;                     *(u32x4*)(MIX + (size_t)r * 1024 + 512 + c0) = oc;
;                     u32x2 pw; pw.x = cvt_pk_bf16(pv4[0], pv4[1]); pw.y = cvt_pk_bf16(pv4[2], pv4[3]);
;                     *(u32x2*)(PB + (size_t)r * PLE + lane * 4) = pw;
	v_add_f32_e32 v148, v148, v150
	ds_bpermute_b32 v150, v84, v148
	s_waitcnt lgkmcnt(0)
	v_add_f32_e32 v148, v148, v150
	ds_bpermute_b32 v150, v85, v148
	s_waitcnt lgkmcnt(0)
	v_add_f32_e32 v148, v148, v150
	v_fmamk_f32 v148, v148, 0x3b000000, v162
	v_mul_f32_e32 v150, 0x4b800000, v148
	v_cmp_gt_f32_e32 vcc, s31, v148
	s_nop 1
	v_cndmask_b32_e32 v148, v148, v150, vcc
	v_rsq_f32_e32 v148, v148
	s_nop 0
	v_mul_f32_e32 v150, 0x45800000, v148
	v_cndmask_b32_e32 v149, v148, v150, vcc
	v_mul_f32_e32 v140, v149, v140
	v_mul_f32_e32 v141, v149, v141
	v_mul_f32_e32 v142, v149, v142
	v_mul_f32_e32 v143, v149, v143
	v_mul_f32_e32 v144, v149, v144
	v_mul_f32_e32 v145, v149, v145
	v_mul_f32_e32 v146, v149, v146
	v_mul_f32_e32 v147, v149, v147
	v_cvt_pk_bf16_f32 v140, v140, v141
	v_cvt_pk_bf16_f32 v141, v142, v143
	v_cvt_pk_bf16_f32 v142, v144, v145
	v_cvt_pk_bf16_f32 v143, v146, v147
	global_store_dwordx4 v[156:157], v[140:143], off offset:2048
	v_lshl_add_u64 v[156:157], v[156:157], 0, s[20:21]
	s_waitcnt vmcnt(10)
	v_lshlrev_b32_e32 v196, 16, v26
	v_and_b32_e32 v197, 0xffff0000, v26
	v_lshlrev_b32_e32 v198, 16, v27
	v_and_b32_e32 v199, 0xffff0000, v27
	v_lshlrev_b32_e32 v200, 16, v28
	v_and_b32_e32 v201, 0xffff0000, v28
	v_lshlrev_b32_e32 v202, 16, v29
	v_and_b32_e32 v203, 0xffff0000, v29
	v_mul_f32_e32 v140, v164, v196
	v_mul_f32_e32 v141, v165, v197
	v_mul_f32_e32 v142, v166, v198
	v_mul_f32_e32 v143, v167, v199
	v_mul_f32_e32 v144, v168, v200
	v_mul_f32_e32 v145, v169, v201
	v_mul_f32_e32 v146, v170, v202
	v_mul_f32_e32 v147, v171, v203
	v_fmac_f32_e32 v140, v172, v188
	v_fmac_f32_e32 v141, v173, v189
	v_fmac_f32_e32 v142, v174, v190
	v_fmac_f32_e32 v143, v175, v191
	v_fmac_f32_e32 v144, v176, v192
	v_fmac_f32_e32 v145, v177, v193
	v_fmac_f32_e32 v146, v178, v194
	v_fmac_f32_e32 v147, v179, v195
	v_fmac_f32_e32 v140, v180, v204
	v_fmac_f32_e32 v141, v181, v205
	v_fmac_f32_e32 v142, v182, v206
	v_fmac_f32_e32 v143, v183, v207
	v_fmac_f32_e32 v144, v184, v208
	v_fmac_f32_e32 v145, v185, v209
	v_fmac_f32_e32 v146, v186, v210
	v_fmac_f32_e32 v147, v187, v211
	v_lshlrev_b32_e32 v150, 16, v10
	v_and_b32_e32 v151, 0xffff0000, v10
	v_mul_f32_e32 v140, v150, v140
	v_mul_f32_e32 v141, v151, v141
	v_lshlrev_b32_e32 v150, 16, v11
	v_and_b32_e32 v151, 0xffff0000, v11
	v_mul_f32_e32 v142, v150, v142
	v_mul_f32_e32 v143, v151, v143
	v_lshlrev_b32_e32 v150, 16, v12
	v_and_b32_e32 v151, 0xffff0000, v12
	v_mul_f32_e32 v144, v150, v144
	v_mul_f32_e32 v145, v151, v145
	v_lshlrev_b32_e32 v150, 16, v13
	v_and_b32_e32 v151, 0xffff0000, v13
	v_mul_f32_e32 v146, v150, v146
	v_mul_f32_e32 v147, v151, v147
	v_mul_f32_e32 v148, v140, v140
	v_fmac_f32_e32 v148, v141, v141
	v_fmac_f32_e32 v148, v142, v142
	v_fmac_f32_e32 v148, v143, v143
	v_fmac_f32_e32 v148, v144, v144
	v_fmac_f32_e32 v148, v145, v145
	v_fmac_f32_e32 v148, v146, v146
	v_fmac_f32_e32 v148, v147, v147
	v_mad_i64_i32 v[152:153], vcc, s41, v221, v[58:59]
	s_add_u32 s41, s41, 1
	global_load_dwordx4 v[10:13], v[152:153], off offset:1536
	global_load_dwordx4 v[26:29], v[152:153], off offset:2560
	ds_bpermute_b32 v150, v80, v148
	s_waitcnt lgkmcnt(0)
	v_add_f32_e32 v148, v148, v150
	ds_bpermute_b32 v150, v81, v148
	s_waitcnt lgkmcnt(0)
	v_add_f32_e32 v148, v148, v150
	ds_bpermute_b32 v150, v82, v148
	s_waitcnt lgkmcnt(0)
	v_add_f32_e32 v148, v148, v150
	ds_bpermute_b32 v150, v83, v148
	s_waitcnt lgkmcnt(0)
	v_add_f32_e32 v148, v148, v150
	ds_bpermute_b32 v150, v84, v148
	s_waitcnt lgkmcnt(0)
	v_add_f32_e32 v148, v148, v150
	ds_bpermute_b32 v150, v85, v148
	s_waitcnt lgkmcnt(0)
	v_add_f32_e32 v148, v148, v150
	v_fmamk_f32 v148, v148, 0x3b000000, v162
	v_mul_f32_e32 v150, 0x4b800000, v148
	v_cmp_gt_f32_e32 vcc, s31, v148
	s_nop 1
	v_cndmask_b32_e32 v148, v148, v150, vcc
	v_rsq_f32_e32 v148, v148
	s_nop 0
	v_mul_f32_e32 v150, 0x45800000, v148
	v_cndmask_b32_e32 v149, v148, v150, vcc
	v_mul_f32_e32 v140, v149, v140
	v_mul_f32_e32 v141, v149, v141
	v_mul_f32_e32 v142, v149, v142
	v_mul_f32_e32 v143, v149, v143
	v_mul_f32_e32 v144, v149, v144
	v_mul_f32_e32 v145, v149, v145
	v_mul_f32_e32 v146, v149, v146
	v_mul_f32_e32 v147, v149, v147
	v_cvt_pk_bf16_f32 v140, v140, v141
	v_cvt_pk_bf16_f32 v141, v142, v143
	v_cvt_pk_bf16_f32 v142, v144, v145
	v_cvt_pk_bf16_f32 v143, v146, v147
	global_store_dwordx4 v[156:157], v[140:143], off
	s_waitcnt vmcnt(10)
	v_lshlrev_b32_e32 v204, 16, v30
	v_and_b32_e32 v205, 0xffff0000, v30
	v_lshlrev_b32_e32 v206, 16, v31
	v_and_b32_e32 v207, 0xffff0000, v31
	v_lshlrev_b32_e32 v208, 16, v32
	v_and_b32_e32 v209, 0xffff0000, v32
	v_lshlrev_b32_e32 v210, 16, v33
	v_and_b32_e32 v211, 0xffff0000, v33
	v_mul_f32_e32 v140, v164, v204
	v_mul_f32_e32 v141, v165, v205
	v_mul_f32_e32 v142, v166, v206
	v_mul_f32_e32 v143, v167, v207
	v_mul_f32_e32 v144, v168, v208
	v_mul_f32_e32 v145, v169, v209
	v_mul_f32_e32 v146, v170, v210
	v_mul_f32_e32 v147, v171, v211
	v_fmac_f32_e32 v140, v172, v196
	v_fmac_f32_e32 v141, v173, v197
	v_fmac_f32_e32 v142, v174, v198
	v_fmac_f32_e32 v143, v175, v199
	v_fmac_f32_e32 v144, v176, v200
	v_fmac_f32_e32 v145, v177, v201
	v_fmac_f32_e32 v146, v178, v202
	v_fmac_f32_e32 v147, v179, v203
	v_fmac_f32_e32 v140, v180, v188
	v_fmac_f32_e32 v141, v181, v189
	v_fmac_f32_e32 v142, v182, v190
	v_fmac_f32_e32 v143, v183, v191
	v_fmac_f32_e32 v144, v184, v192
	v_fmac_f32_e32 v145, v185, v193
	v_fmac_f32_e32 v146, v186, v194
	v_fmac_f32_e32 v147, v187, v195
	v_lshlrev_b32_e32 v150, 16, v14
	v_and_b32_e32 v151, 0xffff0000, v14
	v_mul_f32_e32 v140, v150, v140
	v_mul_f32_e32 v141, v151, v141
	v_lshlrev_b32_e32 v150, 16, v15
	v_and_b32_e32 v151, 0xffff0000, v15
	v_mul_f32_e32 v142, v150, v142
	v_mul_f32_e32 v143, v151, v143
	v_lshlrev_b32_e32 v150, 16, v16
	v_and_b32_e32 v151, 0xffff0000, v16
	v_mul_f32_e32 v144, v150, v144
	v_mul_f32_e32 v145, v151, v145
	v_lshlrev_b32_e32 v150, 16, v17
	v_and_b32_e32 v151, 0xffff0000, v17
	v_mul_f32_e32 v146, v150, v146
	v_mul_f32_e32 v147, v151, v147
	v_mul_f32_e32 v148, v140, v140
	v_fmac_f32_e32 v148, v141, v141
	v_fmac_f32_e32 v148, v142, v142
	v_fmac_f32_e32 v148, v143, v143
	v_fmac_f32_e32 v148, v144, v144
	v_fmac_f32_e32 v148, v145, v145
	v_fmac_f32_e32 v148, v146, v146
	v_fmac_f32_e32 v148, v147, v147
	v_mad_i64_i32 v[152:153], vcc, s41, v221, v[58:59]
	s_add_u32 s41, s41, 1
	global_load_dwordx4 v[14:17], v[152:153], off offset:1536
	global_load_dwordx4 v[30:33], v[152:153], off offset:2560
	ds_bpermute_b32 v150, v80, v148
	s_waitcnt lgkmcnt(0)
; __device__ __forceinline__ unsigned cvt_pk_bf16(float lo, float hi) { unsigned r; asm volatile("v_cvt_pk_bf16_f32 %0, %1, %2" : "=v"(r) : "v"(lo), "v"(hi)); return r; }
; __device__ __forceinline__ float bf_lo(unsigned w) { return __uint_as_float(w << 16); }
; __device__ __forceinline__ float bf_hi(unsigned w) { return __uint_as_float(w & 0xffff0000u); }
; __global__ void __launch_bounds__(512, 2) trunk_fwd(Args args) {
;     ...
;                 for (int rr = 0; rr < 16; ++rr) {
;                     const int r = r0 + rr;
;                     const u32x4 gb = gb_n, gu = gu_n; const f32x4 pv4 = pv_n;
;                     if (rr < 15) { gb_n = *(const u32x4*)(Z + (size_t)(r + 1) * INP + 768 + c0); gu_n = *(const u32x4*)(Z + (size_t)(r + 1) * INP + 1280 + c0);
;                                    pv_n = *(const f32x4*)(pl + (size_t)(r + 1) * PLE + lane * 4); }
;                     float cv[8], uu[8]; float ss = 0.f;
; #pragma unroll
;                     for (int i = 0; i < 4; ++i) {
;                         uu[2 * i] = bf_lo(gu[i]); uu[2 * i + 1] = bf_hi(gu[i]);
;                         cv[2 * i] = bf_lo(gb[i]) * (w0[2 * i] * uu[2 * i] + w1[2 * i] * u1[2 * i] + w2[2 * i] * u2[2 * i]);
;                         cv[2 * i + 1] = bf_hi(gb[i]) * (w0[2 * i + 1] * uu[2 * i + 1] + w1[2 * i + 1] * u1[2 * i + 1] + w2[2 * i + 1] * u2[2 * i + 1]);
;                     }
; #pragma unroll
;                     for (int i = 0; i < 8; ++i) { ss += cv[i] * cv[i]; u2[i] = u1[i]; u1[i] = uu[i]; }
;                     ss = wave_sum(ss);
;                     const float rc = rsqrtf(ss * (1.0f / 512.0f) + EPS);
;                     u32x4 oc;
; #pragma unroll
;                     for (int i = 0; i < 4; ++i) oc[i] = cvt_pk_bf16(cv[2 * i] * rc, cv[2 * i + 1] * rc);
;                     *(u32x4*)(MIX + (size_t)r * 1024 + 512 + c0) = oc;
;                     u32x2 pw; pw.x = cvt_pk_bf16(pv4[0], pv4[1]); pw.y = cvt_pk_bf16(pv4[2], pv4[3]);
;                     *(u32x2*)(PB + (size_t)r * PLE + lane * 4) = pw;
	v_add_f32_e32 v148, v148, v150
	ds_bpermute_b32 v150, v81, v148
	s_waitcnt lgkmcnt(0)
	v_add_f32_e32 v148, v148, v150
	ds_bpermute_b32 v150, v82, v148
	s_waitcnt lgkmcnt(0)
	v_add_f32_e32 v148, v148, v150
	ds_bpermute_b32 v150, v83, v148
	s_waitcnt lgkmcnt(0)
	v_add_f32_e32 v148, v148, v150
	ds_bpermute_b32 v150, v84, v148
	s_waitcnt lgkmcnt(0)
	v_add_f32_e32 v148, v148, v150
	ds_bpermute_b32 v150, v85, v148
	s_waitcnt lgkmcnt(0)
	v_add_f32_e32 v148, v148, v150
	v_fmamk_f32 v148, v148, 0x3b000000, v162
	v_mul_f32_e32 v150, 0x4b800000, v148
	v_cmp_gt_f32_e32 vcc, s31, v148
	s_nop 1
	v_cndmask_b32_e32 v148, v148, v150, vcc
	v_rsq_f32_e32 v148, v148
	s_nop 0
	v_mul_f32_e32 v150, 0x45800000, v148
	v_cndmask_b32_e32 v149, v148, v150, vcc
	v_mul_f32_e32 v140, v149, v140
	v_mul_f32_e32 v141, v149, v141
	v_mul_f32_e32 v142, v149, v142
	v_mul_f32_e32 v143, v149, v143
	v_mul_f32_e32 v144, v149, v144
	v_mul_f32_e32 v145, v149, v145
	v_mul_f32_e32 v146, v149, v146
	v_mul_f32_e32 v147, v149, v147
	v_cvt_pk_bf16_f32 v140, v140, v141
	v_cvt_pk_bf16_f32 v141, v142, v143
	v_cvt_pk_bf16_f32 v142, v144, v145
	v_cvt_pk_bf16_f32 v143, v146, v147
	global_store_dwordx4 v[156:157], v[140:143], off offset:2048
	v_lshl_add_u64 v[156:157], v[156:157], 0, s[20:21]
	s_waitcnt vmcnt(10)
	v_lshlrev_b32_e32 v188, 16, v18
	v_and_b32_e32 v189, 0xffff0000, v18
	v_lshlrev_b32_e32 v190, 16, v19
	v_and_b32_e32 v191, 0xffff0000, v19
	v_lshlrev_b32_e32 v192, 16, v20
	v_and_b32_e32 v193, 0xffff0000, v20
	v_lshlrev_b32_e32 v194, 16, v21
	v_and_b32_e32 v195, 0xffff0000, v21
	v_mul_f32_e32 v140, v164, v188
	v_mul_f32_e32 v141, v165, v189
	v_mul_f32_e32 v142, v166, v190
	v_mul_f32_e32 v143, v167, v191
	v_mul_f32_e32 v144, v168, v192
	v_mul_f32_e32 v145, v169, v193
	v_mul_f32_e32 v146, v170, v194
	v_mul_f32_e32 v147, v171, v195
	v_fmac_f32_e32 v140, v172, v204
	v_fmac_f32_e32 v141, v173, v205
	v_fmac_f32_e32 v142, v174, v206
	v_fmac_f32_e32 v143, v175, v207
	v_fmac_f32_e32 v144, v176, v208
	v_fmac_f32_e32 v145, v177, v209
	v_fmac_f32_e32 v146, v178, v210
	v_fmac_f32_e32 v147, v179, v211
	v_fmac_f32_e32 v140, v180, v196
	v_fmac_f32_e32 v141, v181, v197
	v_fmac_f32_e32 v142, v182, v198
	v_fmac_f32_e32 v143, v183, v199
	v_fmac_f32_e32 v144, v184, v200
	v_fmac_f32_e32 v145, v185, v201
	v_fmac_f32_e32 v146, v186, v202
	v_fmac_f32_e32 v147, v187, v203
	v_lshlrev_b32_e32 v150, 16, v2
	v_and_b32_e32 v151, 0xffff0000, v2
	v_mul_f32_e32 v140, v150, v140
	v_mul_f32_e32 v141, v151, v141
	v_lshlrev_b32_e32 v150, 16, v3
	v_and_b32_e32 v151, 0xffff0000, v3
	v_mul_f32_e32 v142, v150, v142
	v_mul_f32_e32 v143, v151, v143
	v_lshlrev_b32_e32 v150, 16, v4
	v_and_b32_e32 v151, 0xffff0000, v4
	v_mul_f32_e32 v144, v150, v144
	v_mul_f32_e32 v145, v151, v145
	v_lshlrev_b32_e32 v150, 16, v5
	v_and_b32_e32 v151, 0xffff0000, v5
	v_mul_f32_e32 v146, v150, v146
	v_mul_f32_e32 v147, v151, v147
	v_mul_f32_e32 v148, v140, v140
	v_fmac_f32_e32 v148, v141, v141
	v_fmac_f32_e32 v148, v142, v142
	v_fmac_f32_e32 v148, v143, v143
	v_fmac_f32_e32 v148, v144, v144
	v_fmac_f32_e32 v148, v145, v145
	v_fmac_f32_e32 v148, v146, v146
	v_fmac_f32_e32 v148, v147, v147
	ds_bpermute_b32 v150, v80, v148
	s_waitcnt lgkmcnt(0)
	v_add_f32_e32 v148, v148, v150
	ds_bpermute_b32 v150, v81, v148
	s_waitcnt lgkmcnt(0)
	v_add_f32_e32 v148, v148, v150
	ds_bpermute_b32 v150, v82, v148
	s_waitcnt lgkmcnt(0)
	v_add_f32_e32 v148, v148, v150
	ds_bpermute_b32 v150, v83, v148
	s_waitcnt lgkmcnt(0)
	v_add_f32_e32 v148, v148, v150
	ds_bpermute_b32 v150, v84, v148
	s_waitcnt lgkmcnt(0)
	v_add_f32_e32 v148, v148, v150
	ds_bpermute_b32 v150, v85, v148
	s_waitcnt lgkmcnt(0)
	v_add_f32_e32 v148, v148, v150
	v_fmamk_f32 v148, v148, 0x3b000000, v162
	v_mul_f32_e32 v150, 0x4b800000, v148
	v_cmp_gt_f32_e32 vcc, s31, v148
	s_nop 1
	v_cndmask_b32_e32 v148, v148, v150, vcc
	v_rsq_f32_e32 v148, v148
	s_nop 0
	v_mul_f32_e32 v150, 0x45800000, v148
	v_cndmask_b32_e32 v149, v148, v150, vcc
	v_mul_f32_e32 v140, v149, v140
	v_mul_f32_e32 v141, v149, v141
	v_mul_f32_e32 v142, v149, v142
	v_mul_f32_e32 v143, v149, v143
	v_mul_f32_e32 v144, v149, v144
	v_mul_f32_e32 v145, v149, v145
	v_mul_f32_e32 v146, v149, v146
	v_mul_f32_e32 v147, v149, v147
	v_cvt_pk_bf16_f32 v140, v140, v141
	v_cvt_pk_bf16_f32 v141, v142, v143
	v_cvt_pk_bf16_f32 v142, v144, v145
	v_cvt_pk_bf16_f32 v143, v146, v147
	global_store_dwordx4 v[156:157], v[140:143], off
	s_waitcnt vmcnt(8)
	v_lshlrev_b32_e32 v196, 16, v22
	v_and_b32_e32 v197, 0xffff0000, v22
	v_lshlrev_b32_e32 v198, 16, v23
	v_and_b32_e32 v199, 0xffff0000, v23
	v_lshlrev_b32_e32 v200, 16, v24
	v_and_b32_e32 v201, 0xffff0000, v24
	v_lshlrev_b32_e32 v202, 16, v25
	v_and_b32_e32 v203, 0xffff0000, v25
	v_mul_f32_e32 v140, v164, v196
	v_mul_f32_e32 v141, v165, v197
	v_mul_f32_e32 v142, v166, v198
	v_mul_f32_e32 v143, v167, v199
	v_mul_f32_e32 v144, v168, v200
	v_mul_f32_e32 v145, v169, v201
	v_mul_f32_e32 v146, v170, v202
	v_mul_f32_e32 v147, v171, v203
	v_fmac_f32_e32 v140, v172, v188
	v_fmac_f32_e32 v141, v173, v189
	v_fmac_f32_e32 v142, v174, v190
	v_fmac_f32_e32 v143, v175, v191
	v_fmac_f32_e32 v144, v176, v192
	v_fmac_f32_e32 v145, v177, v193
	v_fmac_f32_e32 v146, v178, v194
	v_fmac_f32_e32 v147, v179, v195
	v_fmac_f32_e32 v140, v180, v204
	v_fmac_f32_e32 v141, v181, v205
	v_fmac_f32_e32 v142, v182, v206
	v_fmac_f32_e32 v143, v183, v207
	v_fmac_f32_e32 v144, v184, v208
	v_fmac_f32_e32 v145, v185, v209
	v_fmac_f32_e32 v146, v186, v210
	v_fmac_f32_e32 v147, v187, v211
	v_lshlrev_b32_e32 v150, 16, v6
	v_and_b32_e32 v151, 0xffff0000, v6
	v_mul_f32_e32 v140, v150, v140
	v_mul_f32_e32 v141, v151, v141
	v_lshlrev_b32_e32 v150, 16, v7
	v_and_b32_e32 v151, 0xffff0000, v7
	v_mul_f32_e32 v142, v150, v142
	v_mul_f32_e32 v143, v151, v143
	v_lshlrev_b32_e32 v150, 16, v8
	v_and_b32_e32 v151, 0xffff0000, v8
	v_mul_f32_e32 v144, v150, v144
	v_mul_f32_e32 v145, v151, v145
	v_lshlrev_b32_e32 v150, 16, v9
	v_and_b32_e32 v151, 0xffff0000, v9
	v_mul_f32_e32 v146, v150, v146
	v_mul_f32_e32 v147, v151, v147
	v_mul_f32_e32 v148, v140, v140
	v_fmac_f32_e32 v148, v141, v141
	v_fmac_f32_e32 v148, v142, v142
	v_fmac_f32_e32 v148, v143, v143
	v_fmac_f32_e32 v148, v144, v144
	v_fmac_f32_e32 v148, v145, v145
	v_fmac_f32_e32 v148, v146, v146
	v_fmac_f32_e32 v148, v147, v147
	ds_bpermute_b32 v150, v80, v148
	s_waitcnt lgkmcnt(0)
; __device__ __forceinline__ unsigned cvt_pk_bf16(float lo, float hi) { unsigned r; asm volatile("v_cvt_pk_bf16_f32 %0, %1, %2" : "=v"(r) : "v"(lo), "v"(hi)); return r; }
; __device__ __forceinline__ float bf_lo(unsigned w) { return __uint_as_float(w << 16); }
; __device__ __forceinline__ float bf_hi(unsigned w) { return __uint_as_float(w & 0xffff0000u); }
; __global__ void __launch_bounds__(512, 2) trunk_fwd(Args args) {
;     ...
;                 for (int rr = 0; rr < 16; ++rr) {
;                     const int r = r0 + rr;
;                     const u32x4 gb = gb_n, gu = gu_n; const f32x4 pv4 = pv_n;
;                     if (rr < 15) { gb_n = *(const u32x4*)(Z + (size_t)(r + 1) * INP + 768 + c0); gu_n = *(const u32x4*)(Z + (size_t)(r + 1) * INP + 1280 + c0);
;                                    pv_n = *(const f32x4*)(pl + (size_t)(r + 1) * PLE + lane * 4); }
;                     float cv[8], uu[8]; float ss = 0.f;
; #pragma unroll
;                     for (int i = 0; i < 4; ++i) {
;                         uu[2 * i] = bf_lo(gu[i]); uu[2 * i + 1] = bf_hi(gu[i]);
;                         cv[2 * i] = bf_lo(gb[i]) * (w0[2 * i] * uu[2 * i] + w1[2 * i] * u1[2 * i] + w2[2 * i] * u2[2 * i]);
;                         cv[2 * i + 1] = bf_hi(gb[i]) * (w0[2 * i + 1] * uu[2 * i + 1] + w1[2 * i + 1] * u1[2 * i + 1] + w2[2 * i + 1] * u2[2 * i + 1]);
;                     }
; #pragma unroll
;                     for (int i = 0; i < 8; ++i) { ss += cv[i] * cv[i]; u2[i] = u1[i]; u1[i] = uu[i]; }
;                     ss = wave_sum(ss);
;                     const float rc = rsqrtf(ss * (1.0f / 512.0f) + EPS);
;                     u32x4 oc;
; #pragma unroll
;                     for (int i = 0; i < 4; ++i) oc[i] = cvt_pk_bf16(cv[2 * i] * rc, cv[2 * i + 1] * rc);
;                     *(u32x4*)(MIX + (size_t)r * 1024 + 512 + c0) = oc;
;                     u32x2 pw; pw.x = cvt_pk_bf16(pv4[0], pv4[1]); pw.y = cvt_pk_bf16(pv4[2], pv4[3]);
;                     *(u32x2*)(PB + (size_t)r * PLE + lane * 4) = pw;
	v_add_f32_e32 v148, v148, v150
	ds_bpermute_b32 v150, v81, v148
	s_waitcnt lgkmcnt(0)
	v_add_f32_e32 v148, v148, v150
	ds_bpermute_b32 v150, v82, v148
	s_waitcnt lgkmcnt(0)
	v_add_f32_e32 v148, v148, v150
	ds_bpermute_b32 v150, v83, v148
	s_waitcnt lgkmcnt(0)
	v_add_f32_e32 v148, v148, v150
	ds_bpermute_b32 v150, v84, v148
	s_waitcnt lgkmcnt(0)
	v_add_f32_e32 v148, v148, v150
	ds_bpermute_b32 v150, v85, v148
	s_waitcnt lgkmcnt(0)
	v_add_f32_e32 v148, v148, v150
	v_fmamk_f32 v148, v148, 0x3b000000, v162
	v_mul_f32_e32 v150, 0x4b800000, v148
	v_cmp_gt_f32_e32 vcc, s31, v148
	s_nop 1
	v_cndmask_b32_e32 v148, v148, v150, vcc
	v_rsq_f32_e32 v148, v148
	s_nop 0
	v_mul_f32_e32 v150, 0x45800000, v148
	v_cndmask_b32_e32 v149, v148, v150, vcc
	v_mul_f32_e32 v140, v149, v140
	v_mul_f32_e32 v141, v149, v141
	v_mul_f32_e32 v142, v149, v142
	v_mul_f32_e32 v143, v149, v143
	v_mul_f32_e32 v144, v149, v144
	v_mul_f32_e32 v145, v149, v145
	v_mul_f32_e32 v146, v149, v146
	v_mul_f32_e32 v147, v149, v147
	v_cvt_pk_bf16_f32 v140, v140, v141
	v_cvt_pk_bf16_f32 v141, v142, v143
	v_cvt_pk_bf16_f32 v142, v144, v145
	v_cvt_pk_bf16_f32 v143, v146, v147
	global_store_dwordx4 v[156:157], v[140:143], off offset:2048
	v_lshl_add_u64 v[156:157], v[156:157], 0, s[20:21]
	s_waitcnt vmcnt(6)
	v_lshlrev_b32_e32 v204, 16, v26
	v_and_b32_e32 v205, 0xffff0000, v26
	v_lshlrev_b32_e32 v206, 16, v27
	v_and_b32_e32 v207, 0xffff0000, v27
	v_lshlrev_b32_e32 v208, 16, v28
	v_and_b32_e32 v209, 0xffff0000, v28
	v_lshlrev_b32_e32 v210, 16, v29
	v_and_b32_e32 v211, 0xffff0000, v29
	v_mul_f32_e32 v140, v164, v204
	v_mul_f32_e32 v141, v165, v205
	v_mul_f32_e32 v142, v166, v206
	v_mul_f32_e32 v143, v167, v207
	v_mul_f32_e32 v144, v168, v208
	v_mul_f32_e32 v145, v169, v209
	v_mul_f32_e32 v146, v170, v210
	v_mul_f32_e32 v147, v171, v211
	v_fmac_f32_e32 v140, v172, v196
	v_fmac_f32_e32 v141, v173, v197
	v_fmac_f32_e32 v142, v174, v198
	v_fmac_f32_e32 v143, v175, v199
	v_fmac_f32_e32 v144, v176, v200
	v_fmac_f32_e32 v145, v177, v201
	v_fmac_f32_e32 v146, v178, v202
	v_fmac_f32_e32 v147, v179, v203
	v_fmac_f32_e32 v140, v180, v188
	v_fmac_f32_e32 v141, v181, v189
	v_fmac_f32_e32 v142, v182, v190
	v_fmac_f32_e32 v143, v183, v191
	v_fmac_f32_e32 v144, v184, v192
	v_fmac_f32_e32 v145, v185, v193
	v_fmac_f32_e32 v146, v186, v194
	v_fmac_f32_e32 v147, v187, v195
	v_lshlrev_b32_e32 v150, 16, v10
	v_and_b32_e32 v151, 0xffff0000, v10
	v_mul_f32_e32 v140, v150, v140
	v_mul_f32_e32 v141, v151, v141
	v_lshlrev_b32_e32 v150, 16, v11
	v_and_b32_e32 v151, 0xffff0000, v11
	v_mul_f32_e32 v142, v150, v142
	v_mul_f32_e32 v143, v151, v143
	v_lshlrev_b32_e32 v150, 16, v12
	v_and_b32_e32 v151, 0xffff0000, v12
	v_mul_f32_e32 v144, v150, v144
	v_mul_f32_e32 v145, v151, v145
	v_lshlrev_b32_e32 v150, 16, v13
	v_and_b32_e32 v151, 0xffff0000, v13
	v_mul_f32_e32 v146, v150, v146
	v_mul_f32_e32 v147, v151, v147
	v_mul_f32_e32 v148, v140, v140
	v_fmac_f32_e32 v148, v141, v141
	v_fmac_f32_e32 v148, v142, v142
	v_fmac_f32_e32 v148, v143, v143
	v_fmac_f32_e32 v148, v144, v144
	v_fmac_f32_e32 v148, v145, v145
	v_fmac_f32_e32 v148, v146, v146
	v_fmac_f32_e32 v148, v147, v147
	ds_bpermute_b32 v150, v80, v148
	s_waitcnt lgkmcnt(0)
	v_add_f32_e32 v148, v148, v150
	ds_bpermute_b32 v150, v81, v148
	s_waitcnt lgkmcnt(0)
	v_add_f32_e32 v148, v148, v150
	ds_bpermute_b32 v150, v82, v148
	s_waitcnt lgkmcnt(0)
	v_add_f32_e32 v148, v148, v150
	ds_bpermute_b32 v150, v83, v148
	s_waitcnt lgkmcnt(0)
	v_add_f32_e32 v148, v148, v150
	ds_bpermute_b32 v150, v84, v148
	s_waitcnt lgkmcnt(0)
	v_add_f32_e32 v148, v148, v150
	ds_bpermute_b32 v150, v85, v148
	s_waitcnt lgkmcnt(0)
; __device__ __forceinline__ unsigned cvt_pk_bf16(float lo, float hi) { unsigned r; asm volatile("v_cvt_pk_bf16_f32 %0, %1, %2" : "=v"(r) : "v"(lo), "v"(hi)); return r; }
; __device__ __forceinline__ float bf_lo(unsigned w) { return __uint_as_float(w << 16); }
; __device__ __forceinline__ float bf_hi(unsigned w) { return __uint_as_float(w & 0xffff0000u); }
; __global__ void __launch_bounds__(512, 2) trunk_fwd(Args args) {
;     ...
;                 for (int rr = 0; rr < 16; ++rr) {
;                     const int r = r0 + rr;
;                     const u32x4 gb = gb_n, gu = gu_n; const f32x4 pv4 = pv_n;
;                     if (rr < 15) { gb_n = *(const u32x4*)(Z + (size_t)(r + 1) * INP + 768 + c0); gu_n = *(const u32x4*)(Z + (size_t)(r + 1) * INP + 1280 + c0);
;                                    pv_n = *(const f32x4*)(pl + (size_t)(r + 1) * PLE + lane * 4); }
;                     float cv[8], uu[8]; float ss = 0.f;
; #pragma unroll
;                     for (int i = 0; i < 4; ++i) {
;                         uu[2 * i] = bf_lo(gu[i]); uu[2 * i + 1] = bf_hi(gu[i]);
;                         cv[2 * i] = bf_lo(gb[i]) * (w0[2 * i] * uu[2 * i] + w1[2 * i] * u1[2 * i] + w2[2 * i] * u2[2 * i]);
;                         cv[2 * i + 1] = bf_hi(gb[i]) * (w0[2 * i + 1] * uu[2 * i + 1] + w1[2 * i + 1] * u1[2 * i + 1] + w2[2 * i + 1] * u2[2 * i + 1]);
;                     }
; #pragma unroll
;                     for (int i = 0; i < 8; ++i) { ss += cv[i] * cv[i]; u2[i] = u1[i]; u1[i] = uu[i]; }
;                     ss = wave_sum(ss);
;                     const float rc = rsqrtf(ss * (1.0f / 512.0f) + EPS);
;                     u32x4 oc;
; #pragma unroll
;                     for (int i = 0; i < 4; ++i) oc[i] = cvt_pk_bf16(cv[2 * i] * rc, cv[2 * i + 1] * rc);
;                     *(u32x4*)(MIX + (size_t)r * 1024 + 512 + c0) = oc;
;                     u32x2 pw; pw.x = cvt_pk_bf16(pv4[0], pv4[1]); pw.y = cvt_pk_bf16(pv4[2], pv4[3]);
;                     *(u32x2*)(PB + (size_t)r * PLE + lane * 4) = pw;
;                 }
	v_add_f32_e32 v148, v148, v150
	v_fmamk_f32 v148, v148, 0x3b000000, v162
	v_mul_f32_e32 v150, 0x4b800000, v148
	v_cmp_gt_f32_e32 vcc, s31, v148
	s_nop 1
	v_cndmask_b32_e32 v148, v148, v150, vcc
	v_rsq_f32_e32 v148, v148
	s_nop 0
	v_mul_f32_e32 v150, 0x45800000, v148
	v_cndmask_b32_e32 v149, v148, v150, vcc
	v_mul_f32_e32 v140, v149, v140
	v_mul_f32_e32 v141, v149, v141
	v_mul_f32_e32 v142, v149, v142
	v_mul_f32_e32 v143, v149, v143
	v_mul_f32_e32 v144, v149, v144
	v_mul_f32_e32 v145, v149, v145
	v_mul_f32_e32 v146, v149, v146
	v_mul_f32_e32 v147, v149, v147
	v_cvt_pk_bf16_f32 v140, v140, v141
	v_cvt_pk_bf16_f32 v141, v142, v143
	v_cvt_pk_bf16_f32 v142, v144, v145
	v_cvt_pk_bf16_f32 v143, v146, v147
	global_store_dwordx4 v[156:157], v[140:143], off
	s_waitcnt vmcnt(4)
	v_lshlrev_b32_e32 v188, 16, v30
	v_and_b32_e32 v189, 0xffff0000, v30
	v_lshlrev_b32_e32 v190, 16, v31
	v_and_b32_e32 v191, 0xffff0000, v31
	v_lshlrev_b32_e32 v192, 16, v32
	v_and_b32_e32 v193, 0xffff0000, v32
	v_lshlrev_b32_e32 v194, 16, v33
	v_and_b32_e32 v195, 0xffff0000, v33
	v_mul_f32_e32 v140, v164, v188
	v_mul_f32_e32 v141, v165, v189
	v_mul_f32_e32 v142, v166, v190
	v_mul_f32_e32 v143, v167, v191
	v_mul_f32_e32 v144, v168, v192
	v_mul_f32_e32 v145, v169, v193
	v_mul_f32_e32 v146, v170, v194
	v_mul_f32_e32 v147, v171, v195
	v_fmac_f32_e32 v140, v172, v204
	v_fmac_f32_e32 v141, v173, v205
	v_fmac_f32_e32 v142, v174, v206
	v_fmac_f32_e32 v143, v175, v207
	v_fmac_f32_e32 v144, v176, v208
	v_fmac_f32_e32 v145, v177, v209
	v_fmac_f32_e32 v146, v178, v210
	v_fmac_f32_e32 v147, v179, v211
	v_fmac_f32_e32 v140, v180, v196
	v_fmac_f32_e32 v141, v181, v197
	v_fmac_f32_e32 v142, v182, v198
	v_fmac_f32_e32 v143, v183, v199
	v_fmac_f32_e32 v144, v184, v200
	v_fmac_f32_e32 v145, v185, v201
	v_fmac_f32_e32 v146, v186, v202
	v_fmac_f32_e32 v147, v187, v203
	v_lshlrev_b32_e32 v150, 16, v14
	v_and_b32_e32 v151, 0xffff0000, v14
	v_mul_f32_e32 v140, v150, v140
	v_mul_f32_e32 v141, v151, v141
	v_lshlrev_b32_e32 v150, 16, v15
	v_and_b32_e32 v151, 0xffff0000, v15
	v_mul_f32_e32 v142, v150, v142
	v_mul_f32_e32 v143, v151, v143
	v_lshlrev_b32_e32 v150, 16, v16
	v_and_b32_e32 v151, 0xffff0000, v16
	v_mul_f32_e32 v144, v150, v144
	v_mul_f32_e32 v145, v151, v145
	v_lshlrev_b32_e32 v150, 16, v17
	v_and_b32_e32 v151, 0xffff0000, v17
	v_mul_f32_e32 v146, v150, v146
	v_mul_f32_e32 v147, v151, v147
	v_mul_f32_e32 v148, v140, v140
	v_fmac_f32_e32 v148, v141, v141
	v_fmac_f32_e32 v148, v142, v142
	v_fmac_f32_e32 v148, v143, v143
	v_fmac_f32_e32 v148, v144, v144
	v_fmac_f32_e32 v148, v145, v145
	v_fmac_f32_e32 v148, v146, v146
	v_fmac_f32_e32 v148, v147, v147
	ds_bpermute_b32 v150, v80, v148
	s_waitcnt lgkmcnt(0)
	v_add_f32_e32 v148, v148, v150
	ds_bpermute_b32 v150, v81, v148
	s_waitcnt lgkmcnt(0)
	v_add_f32_e32 v148, v148, v150
	ds_bpermute_b32 v150, v82, v148
	s_waitcnt lgkmcnt(0)
	v_add_f32_e32 v148, v148, v150
	ds_bpermute_b32 v150, v83, v148
	s_waitcnt lgkmcnt(0)
	v_add_f32_e32 v148, v148, v150
	ds_bpermute_b32 v150, v84, v148
	s_waitcnt lgkmcnt(0)
	v_add_f32_e32 v148, v148, v150
	ds_bpermute_b32 v150, v85, v148
	s_waitcnt lgkmcnt(0)
	v_add_f32_e32 v148, v148, v150
	v_fmamk_f32 v148, v148, 0x3b000000, v162
	v_mul_f32_e32 v150, 0x4b800000, v148
	v_cmp_gt_f32_e32 vcc, s31, v148
	s_nop 1
	v_cndmask_b32_e32 v148, v148, v150, vcc
	v_rsq_f32_e32 v148, v148
	s_nop 0
	v_mul_f32_e32 v150, 0x45800000, v148
	v_cndmask_b32_e32 v149, v148, v150, vcc
	v_mul_f32_e32 v140, v149, v140
	v_mul_f32_e32 v141, v149, v141
	v_mul_f32_e32 v142, v149, v142
	v_mul_f32_e32 v143, v149, v143
	v_mul_f32_e32 v144, v149, v144
	v_mul_f32_e32 v145, v149, v145
	v_mul_f32_e32 v146, v149, v146
	v_mul_f32_e32 v147, v149, v147
	v_cvt_pk_bf16_f32 v140, v140, v141
	v_cvt_pk_bf16_f32 v141, v142, v143
	v_cvt_pk_bf16_f32 v142, v144, v145
	v_cvt_pk_bf16_f32 v143, v146, v147
	global_store_dwordx4 v[156:157], v[140:143], off offset:2048
	v_lshl_add_u64 v[156:157], v[156:157], 0, s[20:21]
	s_branch .LBB0_1053
